# P2a tile loop: pass test + candidate append without scalar round trips (v_cmpx mask, per-half counts in VGPRs, v_mbcnt ranks); prune write pass uses v_cmpx
# speedup vs baseline: 1.0163x; 1.0163x over previous
.LBB0_570:
	s_mov_b32 s5, s17
	s_add_i32 s17, s17, -1
	s_mov_b32 s29, s0
	s_mul_i32 s0, s5, s17
	s_lshr_b32 s1, s0, 31
	s_add_i32 s0, s0, s1
	s_ashr_i32 s59, s0, 1
	s_add_i32 s0, s29, -1
	s_cmp_lt_i32 s2, s59
	s_cbranch_scc1 .LBB0_570
	s_and_b64 s[0:1], s[10:11], exec
	s_cselect_b32 s6, 0x2000, 0
	s_lshl_b32 s3, s17, 6
	s_add_i32 s7, s3, s6
	v_add_u32_e32 v2, s7, v173
	v_mad_i64_i32 v[0:1], s[0:1], v2, s4, v[120:121]
	global_load_dwordx4 v[72:75], v[0:1], off offset:3072
	global_load_dwordx4 v[76:79], v[0:1], off offset:3104
	global_load_dwordx4 v[80:83], v[0:1], off offset:3136
	global_load_dwordx4 v[84:87], v[0:1], off offset:3168
	v_or_b32_e32 v0, 4, v2
	v_mad_i64_i32 v[0:1], s[0:1], v0, s4, v[120:121]
	global_load_dwordx4 v[88:91], v[0:1], off offset:3072
	global_load_dwordx4 v[92:95], v[0:1], off offset:3104
	global_load_dwordx4 v[96:99], v[0:1], off offset:3136
	global_load_dwordx4 v[100:103], v[0:1], off offset:3168
	v_add_u32_e32 v0, s7, v174
	v_ashrrev_i32_e32 v1, 31, v0
	v_lshlrev_b64 v[0:1], 5, v[0:1]
	v_lshl_add_u64 v[0:1], s[54:55], 0, v[0:1]
	global_load_dwordx4 v[28:31], v[0:1], off
	global_load_dwordx4 v[12:15], v[0:1], off offset:16
	v_add_u32_e32 v0, s7, v175
	v_ashrrev_i32_e32 v1, 31, v0
	v_lshlrev_b64 v[0:1], 5, v[0:1]
	v_lshl_add_u64 v[0:1], s[54:55], 0, v[0:1]
	global_load_dwordx4 v[24:27], v[0:1], off
	global_load_dwordx4 v[8:11], v[0:1], off offset:16
	v_add_u32_e32 v0, s7, v182
	v_ashrrev_i32_e32 v1, 31, v0
	v_lshlrev_b64 v[0:1], 5, v[0:1]
	v_lshl_add_u64 v[0:1], s[54:55], 0, v[0:1]
	global_load_dwordx4 v[20:23], v[0:1], off
	global_load_dwordx4 v[4:7], v[0:1], off offset:16
	v_add_u32_e32 v0, s7, v183
	v_ashrrev_i32_e32 v1, 31, v0
	v_lshlrev_b64 v[0:1], 5, v[0:1]
	v_lshl_add_u64 v[0:1], s[54:55], 0, v[0:1]
	global_load_dwordx4 v[16:19], v[0:1], off
	s_nop 0
	global_load_dwordx4 v[0:3], v[0:1], off offset:16
	s_and_saveexec_b64 s[0:1], s[36:37]
	ds_write_b32 v185, v65
	s_or_b64 exec, exec, s[0:1]
	s_waitcnt vmcnt(0) lgkmcnt(0)
	s_barrier
	s_and_saveexec_b64 s[0:1], s[38:39]
	v_mov_b32_e32 v32, s21
	v_mov_b32_e32 v33, -1
	ds_write_b32 v32, v33
	s_or_b64 exec, exec, s[0:1]
	v_add_u32_e32 v34, s6, v186
	v_mov_b64_e32 v[32:33], s[52:53]
	v_mad_i64_i32 v[32:33], s[0:1], v34, s4, v[32:33]
	v_lshl_add_u64 v[32:33], v[32:33], 0, v[64:65]
	s_mov_b64 s[0:1], 0x1000
	s_sub_i32 s9, s2, s59
	v_lshl_add_u64 v[138:139], v[32:33], 0, s[0:1]
	s_lshl_b32 s0, s9, 6
	v_mad_i64_i32 v[32:33], s[6:7], s0, v211, v[138:139]
	global_load_dwordx4 v[32:35], v[32:33], off
	s_sub_i32 s1, s62, s60
	s_sub_i32 s2, s5, s9
	s_min_i32 s35, s2, s1
	s_cmp_lt_i32 s35, 1
	s_waitcnt vmcnt(0) lgkmcnt(0)
	ds_write_b128 v187, v[32:35]
	s_waitcnt lgkmcnt(0)
	s_barrier
	s_cbranch_scc1 .LBB0_1067
	v_add_u32_e32 v223, s3, v174
	v_add_u32_e32 v224, s3, v175
	v_add_u32_e32 v225, s3, v182
	v_add_u32_e32 v226, s3, v183
	s_lshl_b32 s1, s59, 6
	s_lshl_b32 s2, s60, 6
	s_lshl_b32 s3, s18, 6
	s_add_i32 s63, s35, s9
	v_pk_mul_f32 v[140:141], v[30:31], 0.5 op_sel_hi:[1,0]
	v_pk_mul_f32 v[142:143], v[28:29], 0.5 op_sel_hi:[1,0]
	v_pk_mul_f32 v[144:145], v[14:15], 0.5 op_sel_hi:[1,0]
	v_pk_mul_f32 v[146:147], v[12:13], 0.5 op_sel_hi:[1,0]
	v_pk_mul_f32 v[148:149], v[26:27], 0.5 op_sel_hi:[1,0]
	v_pk_mul_f32 v[150:151], v[24:25], 0.5 op_sel_hi:[1,0]
	v_pk_mul_f32 v[152:153], v[10:11], 0.5 op_sel_hi:[1,0]
	v_pk_mul_f32 v[154:155], v[8:9], 0.5 op_sel_hi:[1,0]
	v_pk_mul_f32 v[156:157], v[22:23], 0.5 op_sel_hi:[1,0]
	v_pk_mul_f32 v[158:159], v[20:21], 0.5 op_sel_hi:[1,0]
	v_pk_mul_f32 v[160:161], v[6:7], 0.5 op_sel_hi:[1,0]
	v_pk_mul_f32 v[162:163], v[4:5], 0.5 op_sel_hi:[1,0]
	v_pk_mul_f32 v[164:165], v[18:19], 0.5 op_sel_hi:[1,0]
	v_pk_mul_f32 v[166:167], v[16:17], 0.5 op_sel_hi:[1,0]
	v_pk_mul_f32 v[168:169], v[2:3], 0.5 op_sel_hi:[1,0]
	v_pk_mul_f32 v[170:171], v[0:1], 0.5 op_sel_hi:[1,0]
	v_subrev_u32_e32 v227, s1, v172
	s_sub_i32 s66, s2, s3
	v_subrev_u32_e32 v228, s0, v216
	s_sub_i32 s67, 64, s1
	s_mov_b32 s70, 0
	s_mov_b32 s71, 0
	s_mov_b32 s72, 0
	s_mov_b32 s73, 0
	v_mov_b32_e32 v231, v184
	v_mov_b32_e32 v229, v184
	v_mov_b32_e32 v230, v184
	v_mov_b32_e32 v232, v184
	v_mov_b32_e32 v233, v184
	v_mov_b32_e32 v234, v184
	v_mov_b32_e32 v235, v184
	v_mov_b32_e32 v236, v184
	s_mov_b32 s74, 0
	s_mov_b32 s75, 0
	s_mov_b32 s76, 0
	s_mov_b32 s77, 0
	s_mov_b32 s78, 0
	s_mov_b32 s61, 0
	s_mov_b32 s16, 0
	s_mov_b32 s15, 0
	s_mov_b32 s8, 0
	s_mov_b32 s14, 0
	s_mov_b32 s13, 0
	s_mov_b32 s5, 0
	s_mov_b32 s68, 0
	v_lshrrev_b32_e32 v243, 5, v66
	v_lshlrev_b32_e32 v243, 12, v243
	s_add_i32 s0, s33, 0x0
	v_add_u32_e32 v248, s0, v243
	v_mov_b32_e32 v238, v248
	s_add_i32 s0, s33, 0x800
	v_add_u32_e32 v249, s0, v243
	v_mov_b32_e32 v239, v249
	s_add_i32 s0, s33, 0x2000
	v_add_u32_e32 v250, s0, v243
	v_mov_b32_e32 v240, v250
	s_add_i32 s0, s33, 0x2800
	v_add_u32_e32 v237, s0, v243
	v_mov_b32_e32 v241, v237
	v_cndmask_b32_e64 v242, 0, -1, s[40:41]

.LBB0_579:
	s_mul_i32 s0, s68, 0x2400
	v_add_u32_e32 v8, s0, v199
	ds_read_b128 v[0:3], v8
	ds_read_b128 v[4:7], v8 offset:32
	s_cmp_lt_i32 s9, s17
	s_cselect_b64 s[50:51], -1, 0
	v_cndmask_b32_e64 v176, v223, v212, s[50:51]
	s_waitcnt lgkmcnt(0)
	v_mfma_f32_32x32x16_bf16 v[48:63], v[72:75], v[0:3], 0
	v_add_u32_e32 v177, s66, v227
	v_add_u32_e32 v180, 32, v228
	v_mfma_f32_32x32x16_bf16 v[32:47], v[88:91], v[0:3], 0
	v_mfma_f32_32x32x16_bf16 v[48:63], v[76:79], v[4:7], v[48:63]
	v_mfma_f32_32x32x16_bf16 v[32:47], v[92:95], v[4:7], v[32:47]
	ds_read_b128 v[0:3], v8 offset:64
	ds_read_b128 v[4:7], v8 offset:96
	ds_read_b128 v[112:115], v8 offset:4672
	ds_read_b128 v[108:111], v8 offset:4704
	s_waitcnt lgkmcnt(0)
	v_mfma_f32_32x32x16_bf16 v[48:63], v[80:83], v[0:3], v[48:63]
	v_mfma_f32_32x32x16_bf16 v[48:63], v[84:87], v[4:7], v[48:63]
	v_mfma_f32_32x32x16_bf16 v[32:47], v[96:99], v[0:3], v[32:47]
	ds_read_b128 v[116:119], v8 offset:4640
	ds_read_b128 v[0:3], v8 offset:4608
	s_nop 8
	v_add_f32_e64 v8, v48, |v48|
	v_fma_f32 v48, v142, v8, 0
	v_add_f32_e64 v8, v49, |v49|
	v_fmac_f32_e32 v48, v143, v8
	v_add_f32_e64 v8, v50, |v50|
	v_fmac_f32_e32 v48, v140, v8
	v_mfma_f32_32x32x16_bf16 v[32:47], v[100:103], v[4:7], v[32:47]
	v_add_f32_e64 v4, v51, |v51|
	v_fmac_f32_e32 v48, v141, v4
	v_add_f32_e64 v4, v52, |v52|
	v_fmac_f32_e32 v48, v146, v4
	v_add_f32_e64 v4, v53, |v53|
	v_fmac_f32_e32 v48, v147, v4
	v_add_f32_e64 v4, v54, |v54|
	v_fmac_f32_e32 v48, v144, v4
	v_add_f32_e64 v4, v55, |v55|
	s_waitcnt lgkmcnt(0)
	v_mfma_f32_32x32x16_bf16 v[16:31], v[72:75], v[0:3], 0
	v_fmac_f32_e32 v48, v145, v4
	v_mfma_f32_32x32x16_bf16 v[0:15], v[88:91], v[0:3], 0
	v_cndmask_b32_e64 v49, v230, v231, s[40:41]
	v_cmp_le_i32_e32 vcc, v177, v176
	v_ashrrev_i32_e32 v247, 31, v48
	v_bitop3_b32 v244, v247, v48, s93 bitop3:0x36
	v_cndmask_b32_e32 v246, v214, v48, vcc
	v_cmpx_ge_f32_e32 vcc, v246, v49
	v_and_or_b32 v244, v244, s80, v180
	s_nop 0
	v_and_b32_e32 v247, vcc_lo, v242
	v_mbcnt_lo_u32_b32 v243, v247, 0
	v_mbcnt_hi_u32_b32 v243, vcc_hi, v243
	v_lshl_add_u32 v245, v243, 2, v238
	ds_write_b32 v245, v244
	s_mov_b64 exec, -1
	v_bcnt_u32_b32 v246, vcc_lo, 0
	v_bcnt_u32_b32 v247, vcc_hi, 0
	v_cndmask_b32_e64 v246, v247, v246, s[40:41]
	v_lshl_add_u32 v238, v246, 2, v238
	v_add_f32_e64 v50, v56, |v56|
	v_fma_f32 v50, v150, v50, 0
	v_add_f32_e64 v51, v57, |v57|
	v_fmac_f32_e32 v50, v151, v51
	v_add_f32_e64 v51, v58, |v58|
	v_fmac_f32_e32 v50, v148, v51
	v_add_f32_e64 v51, v59, |v59|
	v_mfma_f32_32x32x16_bf16 v[16:31], v[76:79], v[116:119], v[16:31]
	v_fmac_f32_e32 v50, v149, v51
	v_add_f32_e64 v51, v60, |v60|
	v_fmac_f32_e32 v50, v154, v51
	v_add_f32_e64 v51, v61, |v61|
	v_fmac_f32_e32 v50, v155, v51
	v_add_f32_e64 v51, v62, |v62|
	v_fmac_f32_e32 v50, v152, v51
	v_mfma_f32_32x32x16_bf16 v[0:15], v[92:95], v[116:119], v[0:15]
	v_add_f32_e64 v51, v63, |v63|
	v_cndmask_b32_e64 v48, v224, v212, s[50:51]
	v_fmac_f32_e32 v50, v153, v51
	v_cndmask_b32_e64 v51, v232, v229, s[40:41]
	v_cmp_le_i32_e32 vcc, v177, v48
	v_ashrrev_i32_e32 v247, 31, v50
	v_bitop3_b32 v244, v247, v50, s93 bitop3:0x36
	v_cndmask_b32_e32 v246, v214, v50, vcc
	v_cmpx_ge_f32_e32 vcc, v246, v51
	v_and_or_b32 v244, v244, s80, v180
	s_nop 0
	v_and_b32_e32 v247, vcc_lo, v242
	v_mbcnt_lo_u32_b32 v243, v247, 0
	v_mbcnt_hi_u32_b32 v243, vcc_hi, v243
	v_lshl_add_u32 v245, v243, 2, v239
	ds_write_b32 v245, v244
	s_mov_b64 exec, -1
	v_bcnt_u32_b32 v246, vcc_lo, 0
	v_bcnt_u32_b32 v247, vcc_hi, 0
	v_cndmask_b32_e64 v246, v247, v246, s[40:41]
	v_lshl_add_u32 v239, v246, 2, v239
	v_add_f32_e64 v32, v32, |v32|
	v_fma_f32 v32, v158, v32, 0
	v_add_f32_e64 v33, v33, |v33|
	v_fmac_f32_e32 v32, v159, v33
	v_add_f32_e64 v33, v34, |v34|
	v_fmac_f32_e32 v32, v156, v33
	v_add_f32_e64 v33, v35, |v35|
	v_mfma_f32_32x32x16_bf16 v[16:31], v[80:83], v[112:115], v[16:31]
	v_fmac_f32_e32 v32, v157, v33
	v_add_f32_e64 v33, v36, |v36|
	v_fmac_f32_e32 v32, v162, v33
	v_add_f32_e64 v33, v37, |v37|
	v_fmac_f32_e32 v32, v163, v33
	v_add_f32_e64 v33, v38, |v38|
	v_fmac_f32_e32 v32, v160, v33
	v_mfma_f32_32x32x16_bf16 v[0:15], v[96:99], v[112:115], v[0:15]
	v_add_f32_e64 v33, v39, |v39|
	v_cndmask_b32_e64 v50, v225, v212, s[50:51]
	v_fmac_f32_e32 v32, v161, v33
	v_cndmask_b32_e64 v33, v235, v233, s[40:41]
	v_cmp_le_i32_e32 vcc, v177, v50
	v_ashrrev_i32_e32 v247, 31, v32
	v_bitop3_b32 v244, v247, v32, s93 bitop3:0x36
	v_cndmask_b32_e32 v246, v214, v32, vcc
	v_cmpx_ge_f32_e32 vcc, v246, v33
	v_and_or_b32 v244, v244, s80, v180
	s_nop 0
	v_and_b32_e32 v247, vcc_lo, v242
	v_mbcnt_lo_u32_b32 v243, v247, 0
	v_mbcnt_hi_u32_b32 v243, vcc_hi, v243
	v_lshl_add_u32 v245, v243, 2, v240
	ds_write_b32 v245, v244
	s_mov_b64 exec, -1
	v_bcnt_u32_b32 v246, vcc_lo, 0
	v_bcnt_u32_b32 v247, vcc_hi, 0
	v_cndmask_b32_e64 v246, v247, v246, s[40:41]
	v_lshl_add_u32 v240, v246, 2, v240
	v_add_f32_e64 v34, v40, |v40|
	v_fma_f32 v35, v166, v34, 0
	v_add_f32_e64 v34, v41, |v41|
	v_fmac_f32_e32 v35, v167, v34
	v_add_f32_e64 v34, v42, |v42|
	v_fmac_f32_e32 v35, v164, v34
	v_add_f32_e64 v34, v43, |v43|
	v_mfma_f32_32x32x16_bf16 v[16:31], v[84:87], v[108:111], v[16:31]
	v_fmac_f32_e32 v35, v165, v34
	v_add_f32_e64 v34, v44, |v44|
	v_fmac_f32_e32 v35, v170, v34
	v_add_f32_e64 v34, v45, |v45|
	v_fmac_f32_e32 v35, v171, v34
	v_add_f32_e64 v34, v46, |v46|
	v_fmac_f32_e32 v35, v168, v34
	v_mfma_f32_32x32x16_bf16 v[0:15], v[100:103], v[108:111], v[0:15]
	v_add_f32_e64 v34, v47, |v47|
	v_cndmask_b32_e64 v32, v226, v212, s[50:51]
	v_fmac_f32_e32 v35, v169, v34
	v_cndmask_b32_e64 v34, v236, v234, s[40:41]
	v_cmp_le_i32_e32 vcc, v177, v32
	v_ashrrev_i32_e32 v247, 31, v35
	v_bitop3_b32 v244, v247, v35, s93 bitop3:0x36
	v_cndmask_b32_e32 v246, v214, v35, vcc
	v_cmpx_ge_f32_e32 vcc, v246, v34
	v_and_or_b32 v244, v244, s80, v180
	s_nop 0
	v_and_b32_e32 v247, vcc_lo, v242
	v_mbcnt_lo_u32_b32 v243, v247, 0
	v_mbcnt_hi_u32_b32 v243, vcc_hi, v243
	v_lshl_add_u32 v245, v243, 2, v241
	ds_write_b32 v245, v244
	s_mov_b64 exec, -1
	v_bcnt_u32_b32 v246, vcc_lo, 0
	v_bcnt_u32_b32 v247, vcc_hi, 0
	v_cndmask_b32_e64 v246, v247, v246, s[40:41]
	v_lshl_add_u32 v241, v246, 2, v241
	v_add_f32_e64 v16, v16, |v16|
	v_fma_f32 v16, v142, v16, 0
	v_add_f32_e64 v17, v17, |v17|
	v_fmac_f32_e32 v16, v143, v17
	v_add_f32_e64 v17, v18, |v18|
	v_fmac_f32_e32 v16, v140, v17
	v_add_f32_e64 v17, v19, |v19|
	v_fmac_f32_e32 v16, v141, v17
	v_add_f32_e64 v17, v20, |v20|
	v_fmac_f32_e32 v16, v146, v17
	v_add_f32_e64 v17, v21, |v21|
	v_fmac_f32_e32 v16, v147, v17
	v_add_f32_e64 v17, v22, |v22|
	v_fmac_f32_e32 v16, v144, v17
	v_add_f32_e64 v17, v23, |v23|
	v_add_u32_e32 v35, 32, v177
	v_fmac_f32_e32 v16, v145, v17
	v_cmp_le_i32_e32 vcc, v35, v176
	v_ashrrev_i32_e32 v247, 31, v16
	v_bitop3_b32 v244, v247, v16, s93 bitop3:0x36
	v_cndmask_b32_e32 v246, v214, v16, vcc
	v_cmpx_ge_f32_e32 vcc, v246, v49
	v_and_or_b32 v244, v244, s80, v228
	s_nop 0
	v_and_b32_e32 v247, vcc_lo, v242
	v_mbcnt_lo_u32_b32 v243, v247, 0
	v_mbcnt_hi_u32_b32 v243, vcc_hi, v243
	v_lshl_add_u32 v245, v243, 2, v238
	ds_write_b32 v245, v244
	s_mov_b64 exec, -1
	v_bcnt_u32_b32 v246, vcc_lo, 0
	v_bcnt_u32_b32 v247, vcc_hi, 0
	v_cndmask_b32_e64 v246, v247, v246, s[40:41]
	v_lshl_add_u32 v238, v246, 2, v238
	v_add_f32_e64 v16, v24, |v24|
	v_fma_f32 v16, v150, v16, 0
	v_add_f32_e64 v17, v25, |v25|
	v_fmac_f32_e32 v16, v151, v17
	v_add_f32_e64 v17, v26, |v26|
	v_fmac_f32_e32 v16, v148, v17
	v_add_f32_e64 v17, v27, |v27|
	v_fmac_f32_e32 v16, v149, v17
	v_add_f32_e64 v17, v28, |v28|
	v_fmac_f32_e32 v16, v154, v17
	v_add_f32_e64 v17, v29, |v29|
	v_fmac_f32_e32 v16, v155, v17
	v_add_f32_e64 v17, v30, |v30|
	v_fmac_f32_e32 v16, v152, v17
	v_add_f32_e64 v17, v31, |v31|
	v_fmac_f32_e32 v16, v153, v17
	v_cmp_le_i32_e32 vcc, v35, v48
	v_ashrrev_i32_e32 v247, 31, v16
	v_bitop3_b32 v244, v247, v16, s93 bitop3:0x36
	v_cndmask_b32_e32 v246, v214, v16, vcc
	v_cmpx_ge_f32_e32 vcc, v246, v51
	v_and_or_b32 v244, v244, s80, v228
	s_nop 0
	v_and_b32_e32 v247, vcc_lo, v242
	v_mbcnt_lo_u32_b32 v243, v247, 0
	v_mbcnt_hi_u32_b32 v243, vcc_hi, v243
	v_lshl_add_u32 v245, v243, 2, v239
	ds_write_b32 v245, v244
	s_mov_b64 exec, -1
	v_bcnt_u32_b32 v246, vcc_lo, 0
	v_bcnt_u32_b32 v247, vcc_hi, 0
	v_cndmask_b32_e64 v246, v247, v246, s[40:41]
	v_lshl_add_u32 v239, v246, 2, v239
	v_add_f32_e64 v0, v0, |v0|
	v_fma_f32 v0, v158, v0, 0
	v_add_f32_e64 v1, v1, |v1|
	v_fmac_f32_e32 v0, v159, v1
	v_add_f32_e64 v1, v2, |v2|
	v_fmac_f32_e32 v0, v156, v1
	v_add_f32_e64 v1, v3, |v3|
	v_fmac_f32_e32 v0, v157, v1
	v_add_f32_e64 v1, v4, |v4|
	v_fmac_f32_e32 v0, v162, v1
	v_add_f32_e64 v1, v5, |v5|
	v_fmac_f32_e32 v0, v163, v1
	v_add_f32_e64 v1, v6, |v6|
	v_fmac_f32_e32 v0, v160, v1
	v_add_f32_e64 v1, v7, |v7|
	v_fmac_f32_e32 v0, v161, v1
	v_cmp_le_i32_e32 vcc, v35, v50
	v_ashrrev_i32_e32 v247, 31, v0
	v_bitop3_b32 v244, v247, v0, s93 bitop3:0x36
	v_cndmask_b32_e32 v246, v214, v0, vcc
	v_cmpx_ge_f32_e32 vcc, v246, v33
	v_and_or_b32 v244, v244, s80, v228
	s_nop 0
	v_and_b32_e32 v247, vcc_lo, v242
	v_mbcnt_lo_u32_b32 v243, v247, 0
	v_mbcnt_hi_u32_b32 v243, vcc_hi, v243
	v_lshl_add_u32 v245, v243, 2, v240
	ds_write_b32 v245, v244
	s_mov_b64 exec, -1
	v_bcnt_u32_b32 v246, vcc_lo, 0
	v_bcnt_u32_b32 v247, vcc_hi, 0
	v_cndmask_b32_e64 v246, v247, v246, s[40:41]
	v_lshl_add_u32 v240, v246, 2, v240
	v_add_f32_e64 v0, v8, |v8|
	v_fma_f32 v0, v166, v0, 0
	v_add_f32_e64 v1, v9, |v9|
	v_fmac_f32_e32 v0, v167, v1
	v_add_f32_e64 v1, v10, |v10|
	v_fmac_f32_e32 v0, v164, v1
	v_add_f32_e64 v1, v11, |v11|
	v_fmac_f32_e32 v0, v165, v1
	v_add_f32_e64 v1, v12, |v12|
	v_fmac_f32_e32 v0, v170, v1
	v_add_f32_e64 v1, v13, |v13|
	v_fmac_f32_e32 v0, v171, v1
	v_add_f32_e64 v1, v14, |v14|
	v_fmac_f32_e32 v0, v168, v1
	v_add_f32_e64 v1, v15, |v15|
	v_fmac_f32_e32 v0, v169, v1
	v_cmp_le_i32_e32 vcc, v35, v32
	v_ashrrev_i32_e32 v247, 31, v0
	v_bitop3_b32 v244, v247, v0, s93 bitop3:0x36
	v_cndmask_b32_e32 v246, v214, v0, vcc
	v_cmpx_ge_f32_e32 vcc, v246, v34
	v_and_or_b32 v244, v244, s80, v228
	s_nop 0
	v_and_b32_e32 v247, vcc_lo, v242
	v_mbcnt_lo_u32_b32 v243, v247, 0
	v_mbcnt_hi_u32_b32 v243, vcc_hi, v243
	v_lshl_add_u32 v245, v243, 2, v241
	ds_write_b32 v245, v244
	s_mov_b64 exec, -1
	v_bcnt_u32_b32 v246, vcc_lo, 0
	v_bcnt_u32_b32 v247, vcc_hi, 0
	v_cndmask_b32_e64 v246, v247, v246, s[40:41]
	v_lshl_add_u32 v241, v246, 2, v241
	v_sub_u32_e32 v243, v238, v248
	v_sub_u32_e32 v244, v239, v249
	v_sub_u32_e32 v245, v240, v250
	v_sub_u32_e32 v246, v241, v237
	v_max3_u32 v243, v243, v244, v245
	v_max_u32_e32 v243, v243, v246
	v_cmp_lt_u32_e32 vcc, 0x700, v243
	s_cmp_lg_u64 vcc, 0
	s_cselect_b64 s[0:1], -1, 0
	s_and_b64 s[50:51], s[42:43], s[0:1]
	s_and_saveexec_b64 s[22:23], s[50:51]
	v_mov_b32_e32 v0, s21
	v_mov_b32_e32 v1, s9
	ds_write_b32 v0, v1
	s_or_b64 exec, exec, s[22:23]
	s_andn2_b64 vcc, exec, s[2:3]
	s_xor_b32 s68, s68, 1
	s_cbranch_vccnz .LBB0_615
	s_mul_i32 s2, s68, 0x2400
	v_add_u32_e32 v0, s2, v187
	s_waitcnt vmcnt(0)
	ds_write_b128 v0, v[104:107]
.LBB0_615:
	v_mov_b32_e32 v0, s21
	s_waitcnt lgkmcnt(0)
	s_barrier
	ds_read_b32 v0, v0
	s_xor_b64 s[0:1], s[0:1], -1
	s_waitcnt lgkmcnt(0)
	v_cmp_ne_u32_e32 vcc, s9, v0
	s_and_b64 s[0:1], s[0:1], vcc
	s_and_b64 vcc, exec, s[0:1]
	s_cbranch_vccnz .LBB0_1045
	s_nop 0
	v_readlane_b32 s0, v238, 0
	v_readlane_b32 s1, v238, 32
	s_sub_u32 s0, s0, s33
	s_sub_u32 s0, s0, 0x0
	s_lshr_b32 s78, s0, 2
	s_sub_u32 s1, s1, s33
	s_sub_u32 s1, s1, 0x1000
	s_lshr_b32 s16, s1, 2
	v_readlane_b32 s0, v239, 0
	v_readlane_b32 s1, v239, 32
	s_sub_u32 s0, s0, s33
	s_sub_u32 s0, s0, 0x800
	s_lshr_b32 s61, s0, 2
	s_sub_u32 s1, s1, s33
	s_sub_u32 s1, s1, 0x1800
	s_lshr_b32 s15, s1, 2
	v_readlane_b32 s0, v240, 0
	v_readlane_b32 s1, v240, 32
	s_sub_u32 s0, s0, s33
	s_sub_u32 s0, s0, 0x2000
	s_lshr_b32 s8, s0, 2
	s_sub_u32 s1, s1, s33
	s_sub_u32 s1, s1, 0x3000
	s_lshr_b32 s13, s1, 2
	v_readlane_b32 s0, v241, 0
	v_readlane_b32 s1, v241, 32
	s_sub_u32 s0, s0, s33
	s_sub_u32 s0, s0, 0x2800
	s_lshr_b32 s14, s0, 2
	s_sub_u32 s1, s1, s33
	s_sub_u32 s1, s1, 0x3800
	s_lshr_b32 s5, s1, 2
	v_and_b32_e32 v58, 15, v66
	v_lshlrev_b32_e32 v41, 4, v58
	v_sub_u32_e32 v40, v195, v41
	v_lshrrev_b32_e32 v57, 4, v66
	v_lshl_add_u32 v59, v57, 11, s33
	v_add_u32_e32 v60, v59, v41
	s_mov_b32 s22, 0
	s_mov_b32 s23, 0
	s_cmpk_gt_i32 s78, 0x140
	s_cselect_b32 s0, 0xffff, 0
	s_or_b32 s22, s22, s0
	s_cmpk_gt_i32 s61, 0x140
	s_cselect_b32 s0, 0xffff0000, 0
	s_or_b32 s22, s22, s0
	s_cmpk_gt_i32 s16, 0x140
	s_cselect_b32 s0, 0xffff, 0
	s_or_b32 s23, s23, s0
	s_cmpk_gt_i32 s15, 0x140
	s_cselect_b32 s0, 0xffff0000, 0
	s_or_b32 s23, s23, s0
	s_cmp_eq_u64 s[22:23], 0
	s_cbranch_scc1 .Lp2apr0_end
	v_mov_b32_e32 v32, s78
	v_mov_b32_e32 v41, s61
	v_mov_b32_e32 v42, s16
	v_mov_b32_e32 v43, s15
	s_nop 0
	v_mov_b32_dpp v32, v41 quad_perm:[0,1,2,3] row_mask:0x2 bank_mask:0xf
	v_mov_b32_dpp v32, v42 quad_perm:[0,1,2,3] row_mask:0x4 bank_mask:0xf
	v_mov_b32_dpp v32, v43 quad_perm:[0,1,2,3] row_mask:0x8 bank_mask:0xf
	v_mov_b32_e32 v33, s73
	v_mov_b32_e32 v41, s72
	v_mov_b32_e32 v42, s71
	v_mov_b32_e32 v43, s70
	s_nop 0
	v_mov_b32_dpp v33, v41 quad_perm:[0,1,2,3] row_mask:0x2 bank_mask:0xf
	v_mov_b32_dpp v33, v42 quad_perm:[0,1,2,3] row_mask:0x4 bank_mask:0xf
	v_mov_b32_dpp v33, v43 quad_perm:[0,1,2,3] row_mask:0x8 bank_mask:0xf
	ds_read_b128 v[0:3], v60
	ds_read_b128 v[4:7], v60 offset:256
	ds_read_b128 v[8:11], v60 offset:512
	ds_read_b128 v[12:15], v60 offset:768
	ds_read_b128 v[16:19], v60 offset:1024
	ds_read_b128 v[20:23], v60 offset:1280
	ds_read_b128 v[24:27], v60 offset:1536
	ds_read_b128 v[28:31], v60 offset:1792
	v_lshlrev_b32_e32 v41, 2, v58
	v_sub_u32_e32 v41, v32, v41
	s_waitcnt lgkmcnt(0)
	v_mov_b32_e32 v47, 20
	v_subrev_u32_e32 v42, 320, v41
	v_med3_i32 v43, v42, 0, 4
	v_add_u32_e32 v47, v47, v43
	v_cmp_lt_i32_e32 vcc, 0, v42
	v_cmp_lt_i32_e64 s[0:1], 1, v42
	v_cmp_lt_i32_e64 s[2:3], 2, v42
	v_cndmask_b32_e32 v20, 0, v20, vcc
	v_cmp_lt_i32_e32 vcc, 3, v42
	v_cndmask_b32_e64 v21, 0, v21, s[0:1]
	v_cndmask_b32_e64 v22, 0, v22, s[2:3]
	v_cndmask_b32_e32 v23, 0, v23, vcc
	v_subrev_u32_e32 v42, 384, v41
	v_med3_i32 v43, v42, 0, 4
	v_add_u32_e32 v47, v47, v43
	v_cmp_lt_i32_e32 vcc, 0, v42
	v_cmp_lt_i32_e64 s[0:1], 1, v42
	v_cmp_lt_i32_e64 s[2:3], 2, v42
	v_cndmask_b32_e32 v24, 0, v24, vcc
	v_cmp_lt_i32_e32 vcc, 3, v42
	v_cndmask_b32_e64 v25, 0, v25, s[0:1]
	v_cndmask_b32_e64 v26, 0, v26, s[2:3]
	v_cndmask_b32_e32 v27, 0, v27, vcc
	v_subrev_u32_e32 v42, 448, v41
	v_med3_i32 v43, v42, 0, 4
	v_add_u32_e32 v47, v47, v43
	v_cmp_lt_i32_e32 vcc, 0, v42
	v_cmp_lt_i32_e64 s[0:1], 1, v42
	v_cmp_lt_i32_e64 s[2:3], 2, v42
	v_cndmask_b32_e32 v28, 0, v28, vcc
	v_cmp_lt_i32_e32 vcc, 3, v42
	v_cndmask_b32_e64 v29, 0, v29, s[0:1]
	v_cndmask_b32_e64 v30, 0, v30, s[2:3]
	v_cndmask_b32_e32 v31, 0, v31, vcc
	v_max3_u32 v35, v0, v1, v2
	v_max3_u32 v35, v3, v4, v35
	v_max3_u32 v35, v5, v6, v35
	v_max3_u32 v35, v7, v8, v35
	v_max3_u32 v35, v9, v10, v35
	v_max3_u32 v35, v11, v12, v35
	v_max3_u32 v35, v13, v14, v35
	v_max3_u32 v35, v15, v16, v35
	v_max3_u32 v35, v17, v18, v35
	v_max3_u32 v35, v19, v20, v35
	v_max3_u32 v35, v21, v22, v35
	v_max3_u32 v35, v23, v24, v35
	v_max3_u32 v35, v25, v26, v35
	v_max3_u32 v35, v27, v28, v35
	v_max3_u32 v35, v29, v30, v35
	v_max_u32_e32 v35, v31, v35
	s_nop 1
	v_max_u32_dpp v35, v35, v35 row_ror:1 row_mask:0xf bank_mask:0xf
	s_nop 1
	v_max_u32_dpp v35, v35, v35 row_ror:2 row_mask:0xf bank_mask:0xf
	s_nop 1
	v_max_u32_dpp v35, v35, v35 row_ror:4 row_mask:0xf bank_mask:0xf
	s_nop 1
	v_max_u32_dpp v35, v35, v35 row_ror:8 row_mask:0xf bank_mask:0xf
	v_and_b32_e32 v34, 0xffffe000, v33
	v_cmp_eq_u32_e32 vcc, 0, v33
	s_and_b64 vcc, vcc, s[22:23]
	s_cbranch_vccz .Lp2apr0_nomin
	v_add_u32_e32 v41, -1, v0
	v_add_u32_e32 v42, -1, v1
	v_min_u32_e32 v43, v41, v42
	v_add_u32_e32 v41, -1, v2
	v_add_u32_e32 v42, -1, v3
	v_min3_u32 v43, v41, v42, v43
	v_add_u32_e32 v41, -1, v4
	v_add_u32_e32 v42, -1, v5
	v_min3_u32 v43, v41, v42, v43
	v_add_u32_e32 v41, -1, v6
	v_add_u32_e32 v42, -1, v7
	v_min3_u32 v43, v41, v42, v43
	v_add_u32_e32 v41, -1, v8
	v_add_u32_e32 v42, -1, v9
	v_min3_u32 v43, v41, v42, v43
	v_add_u32_e32 v41, -1, v10
	v_add_u32_e32 v42, -1, v11
	v_min3_u32 v43, v41, v42, v43
	v_add_u32_e32 v41, -1, v12
	v_add_u32_e32 v42, -1, v13
	v_min3_u32 v43, v41, v42, v43
	v_add_u32_e32 v41, -1, v14
	v_add_u32_e32 v42, -1, v15
	v_min3_u32 v43, v41, v42, v43
	v_add_u32_e32 v41, -1, v16
	v_add_u32_e32 v42, -1, v17
	v_min3_u32 v43, v41, v42, v43
	v_add_u32_e32 v41, -1, v18
	v_add_u32_e32 v42, -1, v19
	v_min3_u32 v43, v41, v42, v43
	v_add_u32_e32 v41, -1, v20
	v_add_u32_e32 v42, -1, v21
	v_min3_u32 v43, v41, v42, v43
	v_add_u32_e32 v41, -1, v22
	v_add_u32_e32 v42, -1, v23
	v_min3_u32 v43, v41, v42, v43
	v_add_u32_e32 v41, -1, v24
	v_add_u32_e32 v42, -1, v25
	v_min3_u32 v43, v41, v42, v43
	v_add_u32_e32 v41, -1, v26
	v_add_u32_e32 v42, -1, v27
	v_min3_u32 v43, v41, v42, v43
	v_add_u32_e32 v41, -1, v28
	v_add_u32_e32 v42, -1, v29
	v_min3_u32 v43, v41, v42, v43
	v_add_u32_e32 v41, -1, v30
	v_add_u32_e32 v42, -1, v31
	v_min3_u32 v43, v41, v42, v43
	s_nop 1
	v_min_u32_dpp v43, v43, v43 row_ror:1 row_mask:0xf bank_mask:0xf
	s_nop 1
	v_min_u32_dpp v43, v43, v43 row_ror:2 row_mask:0xf bank_mask:0xf
	s_nop 1
	v_min_u32_dpp v43, v43, v43 row_ror:4 row_mask:0xf bank_mask:0xf
	s_nop 1
	v_min_u32_dpp v43, v43, v43 row_ror:8 row_mask:0xf bank_mask:0xf
	v_add_u32_e32 v43, 1, v43
	v_cmp_eq_u32_e32 vcc, 0, v33
	s_nop 1
	v_cndmask_b32_e32 v34, v34, v43, vcc

.Lp2apr0_iter:
	v_sub_u32_e32 v38, v35, v34
	v_or_b32_e32 v41, 1, v38
	v_ffbh_u32_e32 v41, v41
	v_sub_u32_e32 v41, 26, v41
	v_max_i32_e32 v39, 0, v41
	v_mov_b32_e32 v36, 0
	v_or_b32_e32 v42, 32, v36
	v_lshlrev_b32_e32 v41, v39, v42
	v_add_u32_e64 v43, v34, v41 clamp
	v_mov_b32_e32 v44, 0
	v_cmp_ge_u32_e32 vcc, v0, v43
	v_cmp_ge_u32_e64 s[0:1], v1, v43
	v_cmp_ge_u32_e64 s[2:3], v2, v43
	v_addc_co_u32_e64 v44, vcc, 0, v44, vcc
	v_cmp_ge_u32_e32 vcc, v3, v43
	v_addc_co_u32_e64 v44, s[0:1], 0, v44, s[0:1]
	v_cmp_ge_u32_e64 s[0:1], v4, v43
	v_addc_co_u32_e64 v44, s[2:3], 0, v44, s[2:3]
	v_cmp_ge_u32_e64 s[2:3], v5, v43
	v_addc_co_u32_e64 v44, vcc, 0, v44, vcc
	v_cmp_ge_u32_e32 vcc, v6, v43
	v_addc_co_u32_e64 v44, s[0:1], 0, v44, s[0:1]
	v_cmp_ge_u32_e64 s[0:1], v7, v43
	v_addc_co_u32_e64 v44, s[2:3], 0, v44, s[2:3]
	v_cmp_ge_u32_e64 s[2:3], v8, v43
	v_addc_co_u32_e64 v44, vcc, 0, v44, vcc
	v_cmp_ge_u32_e32 vcc, v9, v43
	v_addc_co_u32_e64 v44, s[0:1], 0, v44, s[0:1]
	v_cmp_ge_u32_e64 s[0:1], v10, v43
	v_addc_co_u32_e64 v44, s[2:3], 0, v44, s[2:3]
	v_cmp_ge_u32_e64 s[2:3], v11, v43
	v_addc_co_u32_e64 v44, vcc, 0, v44, vcc
	v_cmp_ge_u32_e32 vcc, v12, v43
	v_addc_co_u32_e64 v44, s[0:1], 0, v44, s[0:1]
	v_cmp_ge_u32_e64 s[0:1], v13, v43
	v_addc_co_u32_e64 v44, s[2:3], 0, v44, s[2:3]
	v_cmp_ge_u32_e64 s[2:3], v14, v43
	v_addc_co_u32_e64 v44, vcc, 0, v44, vcc
	v_cmp_ge_u32_e32 vcc, v15, v43
	v_addc_co_u32_e64 v44, s[0:1], 0, v44, s[0:1]
	v_cmp_ge_u32_e64 s[0:1], v16, v43
	v_addc_co_u32_e64 v44, s[2:3], 0, v44, s[2:3]
	v_cmp_ge_u32_e64 s[2:3], v17, v43
	v_addc_co_u32_e64 v44, vcc, 0, v44, vcc
	v_cmp_ge_u32_e32 vcc, v18, v43
	v_addc_co_u32_e64 v44, s[0:1], 0, v44, s[0:1]
	v_cmp_ge_u32_e64 s[0:1], v19, v43
	v_addc_co_u32_e64 v44, s[2:3], 0, v44, s[2:3]
	v_cmp_ge_u32_e64 s[2:3], v20, v43
	v_addc_co_u32_e64 v44, vcc, 0, v44, vcc
	v_cmp_ge_u32_e32 vcc, v21, v43
	v_addc_co_u32_e64 v44, s[0:1], 0, v44, s[0:1]
	v_cmp_ge_u32_e64 s[0:1], v22, v43
	v_addc_co_u32_e64 v44, s[2:3], 0, v44, s[2:3]
	v_cmp_ge_u32_e64 s[2:3], v23, v43
	v_addc_co_u32_e64 v44, vcc, 0, v44, vcc
	v_cmp_ge_u32_e32 vcc, v24, v43
	v_addc_co_u32_e64 v44, s[0:1], 0, v44, s[0:1]
	v_cmp_ge_u32_e64 s[0:1], v25, v43
	v_addc_co_u32_e64 v44, s[2:3], 0, v44, s[2:3]
	v_cmp_ge_u32_e64 s[2:3], v26, v43
	v_addc_co_u32_e64 v44, vcc, 0, v44, vcc
	v_cmp_ge_u32_e32 vcc, v27, v43
	v_addc_co_u32_e64 v44, s[0:1], 0, v44, s[0:1]
	v_cmp_ge_u32_e64 s[0:1], v28, v43
	v_addc_co_u32_e64 v44, s[2:3], 0, v44, s[2:3]
	v_cmp_ge_u32_e64 s[2:3], v29, v43
	v_addc_co_u32_e64 v44, vcc, 0, v44, vcc
	v_cmp_ge_u32_e32 vcc, v30, v43
	v_addc_co_u32_e64 v44, s[0:1], 0, v44, s[0:1]
	v_cmp_ge_u32_e64 s[0:1], v31, v43
	v_addc_co_u32_e64 v44, s[2:3], 0, v44, s[2:3]
	v_addc_co_u32_e64 v44, vcc, 0, v44, vcc
	v_addc_co_u32_e64 v44, s[0:1], 0, v44, s[0:1]
	v_mov_b32_e32 v45, v44
	s_nop 1
	v_add_u32_dpp v45, v45, v45 row_ror:1 row_mask:0xf bank_mask:0xf
	s_nop 1
	v_add_u32_dpp v45, v45, v45 row_ror:2 row_mask:0xf bank_mask:0xf
	s_nop 1
	v_add_u32_dpp v45, v45, v45 row_ror:4 row_mask:0xf bank_mask:0xf
	s_nop 1
	v_add_u32_dpp v45, v45, v45 row_ror:8 row_mask:0xf bank_mask:0xf
	s_nop 0
	v_cmp_le_u32_e32 vcc, 0x100, v45
	s_nop 1
	v_cndmask_b32_e32 v36, v36, v42, vcc
	v_cndmask_b32_e32 v46, v46, v45, vcc
	v_cndmask_b32_e32 v47, v47, v44, vcc
	v_or_b32_e32 v42, 16, v36
	v_lshlrev_b32_e32 v41, v39, v42
	v_add_u32_e64 v43, v34, v41 clamp
	v_mov_b32_e32 v44, 0
	v_cmp_ge_u32_e32 vcc, v0, v43
	v_cmp_ge_u32_e64 s[0:1], v1, v43
	v_cmp_ge_u32_e64 s[2:3], v2, v43
	v_addc_co_u32_e64 v44, vcc, 0, v44, vcc
	v_cmp_ge_u32_e32 vcc, v3, v43
	v_addc_co_u32_e64 v44, s[0:1], 0, v44, s[0:1]
	v_cmp_ge_u32_e64 s[0:1], v4, v43
	v_addc_co_u32_e64 v44, s[2:3], 0, v44, s[2:3]
	v_cmp_ge_u32_e64 s[2:3], v5, v43
	v_addc_co_u32_e64 v44, vcc, 0, v44, vcc
	v_cmp_ge_u32_e32 vcc, v6, v43
	v_addc_co_u32_e64 v44, s[0:1], 0, v44, s[0:1]
	v_cmp_ge_u32_e64 s[0:1], v7, v43
	v_addc_co_u32_e64 v44, s[2:3], 0, v44, s[2:3]
	v_cmp_ge_u32_e64 s[2:3], v8, v43
	v_addc_co_u32_e64 v44, vcc, 0, v44, vcc
	v_cmp_ge_u32_e32 vcc, v9, v43
	v_addc_co_u32_e64 v44, s[0:1], 0, v44, s[0:1]
	v_cmp_ge_u32_e64 s[0:1], v10, v43
	v_addc_co_u32_e64 v44, s[2:3], 0, v44, s[2:3]
	v_cmp_ge_u32_e64 s[2:3], v11, v43
	v_addc_co_u32_e64 v44, vcc, 0, v44, vcc
	v_cmp_ge_u32_e32 vcc, v12, v43
	v_addc_co_u32_e64 v44, s[0:1], 0, v44, s[0:1]
	v_cmp_ge_u32_e64 s[0:1], v13, v43
	v_addc_co_u32_e64 v44, s[2:3], 0, v44, s[2:3]
	v_cmp_ge_u32_e64 s[2:3], v14, v43
	v_addc_co_u32_e64 v44, vcc, 0, v44, vcc
	v_cmp_ge_u32_e32 vcc, v15, v43
	v_addc_co_u32_e64 v44, s[0:1], 0, v44, s[0:1]
	v_cmp_ge_u32_e64 s[0:1], v16, v43
	v_addc_co_u32_e64 v44, s[2:3], 0, v44, s[2:3]
	v_cmp_ge_u32_e64 s[2:3], v17, v43
	v_addc_co_u32_e64 v44, vcc, 0, v44, vcc
	v_cmp_ge_u32_e32 vcc, v18, v43
	v_addc_co_u32_e64 v44, s[0:1], 0, v44, s[0:1]
	v_cmp_ge_u32_e64 s[0:1], v19, v43
	v_addc_co_u32_e64 v44, s[2:3], 0, v44, s[2:3]
	v_cmp_ge_u32_e64 s[2:3], v20, v43
	v_addc_co_u32_e64 v44, vcc, 0, v44, vcc
	v_cmp_ge_u32_e32 vcc, v21, v43
	v_addc_co_u32_e64 v44, s[0:1], 0, v44, s[0:1]
	v_cmp_ge_u32_e64 s[0:1], v22, v43
	v_addc_co_u32_e64 v44, s[2:3], 0, v44, s[2:3]
	v_cmp_ge_u32_e64 s[2:3], v23, v43
	v_addc_co_u32_e64 v44, vcc, 0, v44, vcc
	v_cmp_ge_u32_e32 vcc, v24, v43
	v_addc_co_u32_e64 v44, s[0:1], 0, v44, s[0:1]
	v_cmp_ge_u32_e64 s[0:1], v25, v43
	v_addc_co_u32_e64 v44, s[2:3], 0, v44, s[2:3]
	v_cmp_ge_u32_e64 s[2:3], v26, v43
	v_addc_co_u32_e64 v44, vcc, 0, v44, vcc
	v_cmp_ge_u32_e32 vcc, v27, v43
	v_addc_co_u32_e64 v44, s[0:1], 0, v44, s[0:1]
	v_cmp_ge_u32_e64 s[0:1], v28, v43
	v_addc_co_u32_e64 v44, s[2:3], 0, v44, s[2:3]
	v_cmp_ge_u32_e64 s[2:3], v29, v43
	v_addc_co_u32_e64 v44, vcc, 0, v44, vcc
	v_cmp_ge_u32_e32 vcc, v30, v43
	v_addc_co_u32_e64 v44, s[0:1], 0, v44, s[0:1]
	v_cmp_ge_u32_e64 s[0:1], v31, v43
	v_addc_co_u32_e64 v44, s[2:3], 0, v44, s[2:3]
	v_addc_co_u32_e64 v44, vcc, 0, v44, vcc
	v_addc_co_u32_e64 v44, s[0:1], 0, v44, s[0:1]
	v_mov_b32_e32 v45, v44
	s_nop 1
	v_add_u32_dpp v45, v45, v45 row_ror:1 row_mask:0xf bank_mask:0xf
	s_nop 1
	v_add_u32_dpp v45, v45, v45 row_ror:2 row_mask:0xf bank_mask:0xf
	s_nop 1
	v_add_u32_dpp v45, v45, v45 row_ror:4 row_mask:0xf bank_mask:0xf
	s_nop 1
	v_add_u32_dpp v45, v45, v45 row_ror:8 row_mask:0xf bank_mask:0xf
	s_nop 0
	v_cmp_le_u32_e32 vcc, 0x100, v45
	s_nop 1
	v_cndmask_b32_e32 v36, v36, v42, vcc
	v_cndmask_b32_e32 v46, v46, v45, vcc
	v_cndmask_b32_e32 v47, v47, v44, vcc
	v_or_b32_e32 v42, 8, v36
	v_lshlrev_b32_e32 v41, v39, v42
	v_add_u32_e64 v43, v34, v41 clamp
	v_mov_b32_e32 v44, 0
	v_cmp_ge_u32_e32 vcc, v0, v43
	v_cmp_ge_u32_e64 s[0:1], v1, v43
	v_cmp_ge_u32_e64 s[2:3], v2, v43
	v_addc_co_u32_e64 v44, vcc, 0, v44, vcc
	v_cmp_ge_u32_e32 vcc, v3, v43
	v_addc_co_u32_e64 v44, s[0:1], 0, v44, s[0:1]
	v_cmp_ge_u32_e64 s[0:1], v4, v43
	v_addc_co_u32_e64 v44, s[2:3], 0, v44, s[2:3]
	v_cmp_ge_u32_e64 s[2:3], v5, v43
	v_addc_co_u32_e64 v44, vcc, 0, v44, vcc
	v_cmp_ge_u32_e32 vcc, v6, v43
	v_addc_co_u32_e64 v44, s[0:1], 0, v44, s[0:1]
	v_cmp_ge_u32_e64 s[0:1], v7, v43
	v_addc_co_u32_e64 v44, s[2:3], 0, v44, s[2:3]
	v_cmp_ge_u32_e64 s[2:3], v8, v43
	v_addc_co_u32_e64 v44, vcc, 0, v44, vcc
	v_cmp_ge_u32_e32 vcc, v9, v43
	v_addc_co_u32_e64 v44, s[0:1], 0, v44, s[0:1]
	v_cmp_ge_u32_e64 s[0:1], v10, v43
	v_addc_co_u32_e64 v44, s[2:3], 0, v44, s[2:3]
	v_cmp_ge_u32_e64 s[2:3], v11, v43
	v_addc_co_u32_e64 v44, vcc, 0, v44, vcc
	v_cmp_ge_u32_e32 vcc, v12, v43
	v_addc_co_u32_e64 v44, s[0:1], 0, v44, s[0:1]
	v_cmp_ge_u32_e64 s[0:1], v13, v43
	v_addc_co_u32_e64 v44, s[2:3], 0, v44, s[2:3]
	v_cmp_ge_u32_e64 s[2:3], v14, v43
	v_addc_co_u32_e64 v44, vcc, 0, v44, vcc
	v_cmp_ge_u32_e32 vcc, v15, v43
	v_addc_co_u32_e64 v44, s[0:1], 0, v44, s[0:1]
	v_cmp_ge_u32_e64 s[0:1], v16, v43
	v_addc_co_u32_e64 v44, s[2:3], 0, v44, s[2:3]
	v_cmp_ge_u32_e64 s[2:3], v17, v43
	v_addc_co_u32_e64 v44, vcc, 0, v44, vcc
	v_cmp_ge_u32_e32 vcc, v18, v43
	v_addc_co_u32_e64 v44, s[0:1], 0, v44, s[0:1]
	v_cmp_ge_u32_e64 s[0:1], v19, v43
	v_addc_co_u32_e64 v44, s[2:3], 0, v44, s[2:3]
	v_cmp_ge_u32_e64 s[2:3], v20, v43
	v_addc_co_u32_e64 v44, vcc, 0, v44, vcc
	v_cmp_ge_u32_e32 vcc, v21, v43
	v_addc_co_u32_e64 v44, s[0:1], 0, v44, s[0:1]
	v_cmp_ge_u32_e64 s[0:1], v22, v43
	v_addc_co_u32_e64 v44, s[2:3], 0, v44, s[2:3]
	v_cmp_ge_u32_e64 s[2:3], v23, v43
	v_addc_co_u32_e64 v44, vcc, 0, v44, vcc
	v_cmp_ge_u32_e32 vcc, v24, v43
	v_addc_co_u32_e64 v44, s[0:1], 0, v44, s[0:1]
	v_cmp_ge_u32_e64 s[0:1], v25, v43
	v_addc_co_u32_e64 v44, s[2:3], 0, v44, s[2:3]
	v_cmp_ge_u32_e64 s[2:3], v26, v43
	v_addc_co_u32_e64 v44, vcc, 0, v44, vcc
	v_cmp_ge_u32_e32 vcc, v27, v43
	v_addc_co_u32_e64 v44, s[0:1], 0, v44, s[0:1]
	v_cmp_ge_u32_e64 s[0:1], v28, v43
	v_addc_co_u32_e64 v44, s[2:3], 0, v44, s[2:3]
	v_cmp_ge_u32_e64 s[2:3], v29, v43
	v_addc_co_u32_e64 v44, vcc, 0, v44, vcc
	v_cmp_ge_u32_e32 vcc, v30, v43
	v_addc_co_u32_e64 v44, s[0:1], 0, v44, s[0:1]
	v_cmp_ge_u32_e64 s[0:1], v31, v43
	v_addc_co_u32_e64 v44, s[2:3], 0, v44, s[2:3]
	v_addc_co_u32_e64 v44, vcc, 0, v44, vcc
	v_addc_co_u32_e64 v44, s[0:1], 0, v44, s[0:1]
	v_mov_b32_e32 v45, v44
	s_nop 1
	v_add_u32_dpp v45, v45, v45 row_ror:1 row_mask:0xf bank_mask:0xf
	s_nop 1
	v_add_u32_dpp v45, v45, v45 row_ror:2 row_mask:0xf bank_mask:0xf
	s_nop 1
	v_add_u32_dpp v45, v45, v45 row_ror:4 row_mask:0xf bank_mask:0xf
	s_nop 1
	v_add_u32_dpp v45, v45, v45 row_ror:8 row_mask:0xf bank_mask:0xf
	s_nop 0
	v_cmp_le_u32_e32 vcc, 0x100, v45
	s_nop 1
	v_cndmask_b32_e32 v36, v36, v42, vcc
	v_cndmask_b32_e32 v46, v46, v45, vcc
	v_cndmask_b32_e32 v47, v47, v44, vcc
	v_or_b32_e32 v42, 4, v36
	v_lshlrev_b32_e32 v41, v39, v42
	v_add_u32_e64 v43, v34, v41 clamp
	v_mov_b32_e32 v44, 0
	v_cmp_ge_u32_e32 vcc, v0, v43
	v_cmp_ge_u32_e64 s[0:1], v1, v43
	v_cmp_ge_u32_e64 s[2:3], v2, v43
	v_addc_co_u32_e64 v44, vcc, 0, v44, vcc
	v_cmp_ge_u32_e32 vcc, v3, v43
	v_addc_co_u32_e64 v44, s[0:1], 0, v44, s[0:1]
	v_cmp_ge_u32_e64 s[0:1], v4, v43
	v_addc_co_u32_e64 v44, s[2:3], 0, v44, s[2:3]
	v_cmp_ge_u32_e64 s[2:3], v5, v43
	v_addc_co_u32_e64 v44, vcc, 0, v44, vcc
	v_cmp_ge_u32_e32 vcc, v6, v43
	v_addc_co_u32_e64 v44, s[0:1], 0, v44, s[0:1]
	v_cmp_ge_u32_e64 s[0:1], v7, v43
	v_addc_co_u32_e64 v44, s[2:3], 0, v44, s[2:3]
	v_cmp_ge_u32_e64 s[2:3], v8, v43
	v_addc_co_u32_e64 v44, vcc, 0, v44, vcc
	v_cmp_ge_u32_e32 vcc, v9, v43
	v_addc_co_u32_e64 v44, s[0:1], 0, v44, s[0:1]
	v_cmp_ge_u32_e64 s[0:1], v10, v43
	v_addc_co_u32_e64 v44, s[2:3], 0, v44, s[2:3]
	v_cmp_ge_u32_e64 s[2:3], v11, v43
	v_addc_co_u32_e64 v44, vcc, 0, v44, vcc
	v_cmp_ge_u32_e32 vcc, v12, v43
	v_addc_co_u32_e64 v44, s[0:1], 0, v44, s[0:1]
	v_cmp_ge_u32_e64 s[0:1], v13, v43
	v_addc_co_u32_e64 v44, s[2:3], 0, v44, s[2:3]
	v_cmp_ge_u32_e64 s[2:3], v14, v43
	v_addc_co_u32_e64 v44, vcc, 0, v44, vcc
	v_cmp_ge_u32_e32 vcc, v15, v43
	v_addc_co_u32_e64 v44, s[0:1], 0, v44, s[0:1]
	v_cmp_ge_u32_e64 s[0:1], v16, v43
	v_addc_co_u32_e64 v44, s[2:3], 0, v44, s[2:3]
	v_cmp_ge_u32_e64 s[2:3], v17, v43
	v_addc_co_u32_e64 v44, vcc, 0, v44, vcc
	v_cmp_ge_u32_e32 vcc, v18, v43
	v_addc_co_u32_e64 v44, s[0:1], 0, v44, s[0:1]
	v_cmp_ge_u32_e64 s[0:1], v19, v43
	v_addc_co_u32_e64 v44, s[2:3], 0, v44, s[2:3]
	v_cmp_ge_u32_e64 s[2:3], v20, v43
	v_addc_co_u32_e64 v44, vcc, 0, v44, vcc
	v_cmp_ge_u32_e32 vcc, v21, v43
	v_addc_co_u32_e64 v44, s[0:1], 0, v44, s[0:1]
	v_cmp_ge_u32_e64 s[0:1], v22, v43
	v_addc_co_u32_e64 v44, s[2:3], 0, v44, s[2:3]
	v_cmp_ge_u32_e64 s[2:3], v23, v43
	v_addc_co_u32_e64 v44, vcc, 0, v44, vcc
	v_cmp_ge_u32_e32 vcc, v24, v43
	v_addc_co_u32_e64 v44, s[0:1], 0, v44, s[0:1]
	v_cmp_ge_u32_e64 s[0:1], v25, v43
	v_addc_co_u32_e64 v44, s[2:3], 0, v44, s[2:3]
	v_cmp_ge_u32_e64 s[2:3], v26, v43
	v_addc_co_u32_e64 v44, vcc, 0, v44, vcc
	v_cmp_ge_u32_e32 vcc, v27, v43
	v_addc_co_u32_e64 v44, s[0:1], 0, v44, s[0:1]
	v_cmp_ge_u32_e64 s[0:1], v28, v43
	v_addc_co_u32_e64 v44, s[2:3], 0, v44, s[2:3]
	v_cmp_ge_u32_e64 s[2:3], v29, v43
	v_addc_co_u32_e64 v44, vcc, 0, v44, vcc
	v_cmp_ge_u32_e32 vcc, v30, v43
	v_addc_co_u32_e64 v44, s[0:1], 0, v44, s[0:1]
	v_cmp_ge_u32_e64 s[0:1], v31, v43
	v_addc_co_u32_e64 v44, s[2:3], 0, v44, s[2:3]
	v_addc_co_u32_e64 v44, vcc, 0, v44, vcc
	v_addc_co_u32_e64 v44, s[0:1], 0, v44, s[0:1]
	v_mov_b32_e32 v45, v44
	s_nop 1
	v_add_u32_dpp v45, v45, v45 row_ror:1 row_mask:0xf bank_mask:0xf
	s_nop 1
	v_add_u32_dpp v45, v45, v45 row_ror:2 row_mask:0xf bank_mask:0xf
	s_nop 1
	v_add_u32_dpp v45, v45, v45 row_ror:4 row_mask:0xf bank_mask:0xf
	s_nop 1
	v_add_u32_dpp v45, v45, v45 row_ror:8 row_mask:0xf bank_mask:0xf
	s_nop 0
	v_cmp_le_u32_e32 vcc, 0x100, v45
	s_nop 1
	v_cndmask_b32_e32 v36, v36, v42, vcc
	v_cndmask_b32_e32 v46, v46, v45, vcc
	v_cndmask_b32_e32 v47, v47, v44, vcc
	v_or_b32_e32 v42, 2, v36
	v_lshlrev_b32_e32 v41, v39, v42
	v_add_u32_e64 v43, v34, v41 clamp
	v_mov_b32_e32 v44, 0
	v_cmp_ge_u32_e32 vcc, v0, v43
	v_cmp_ge_u32_e64 s[0:1], v1, v43
	v_cmp_ge_u32_e64 s[2:3], v2, v43
	v_addc_co_u32_e64 v44, vcc, 0, v44, vcc
	v_cmp_ge_u32_e32 vcc, v3, v43
	v_addc_co_u32_e64 v44, s[0:1], 0, v44, s[0:1]
	v_cmp_ge_u32_e64 s[0:1], v4, v43
	v_addc_co_u32_e64 v44, s[2:3], 0, v44, s[2:3]
	v_cmp_ge_u32_e64 s[2:3], v5, v43
	v_addc_co_u32_e64 v44, vcc, 0, v44, vcc
	v_cmp_ge_u32_e32 vcc, v6, v43
	v_addc_co_u32_e64 v44, s[0:1], 0, v44, s[0:1]
	v_cmp_ge_u32_e64 s[0:1], v7, v43
	v_addc_co_u32_e64 v44, s[2:3], 0, v44, s[2:3]
	v_cmp_ge_u32_e64 s[2:3], v8, v43
	v_addc_co_u32_e64 v44, vcc, 0, v44, vcc
	v_cmp_ge_u32_e32 vcc, v9, v43
	v_addc_co_u32_e64 v44, s[0:1], 0, v44, s[0:1]
	v_cmp_ge_u32_e64 s[0:1], v10, v43
	v_addc_co_u32_e64 v44, s[2:3], 0, v44, s[2:3]
	v_cmp_ge_u32_e64 s[2:3], v11, v43
	v_addc_co_u32_e64 v44, vcc, 0, v44, vcc
	v_cmp_ge_u32_e32 vcc, v12, v43
	v_addc_co_u32_e64 v44, s[0:1], 0, v44, s[0:1]
	v_cmp_ge_u32_e64 s[0:1], v13, v43
	v_addc_co_u32_e64 v44, s[2:3], 0, v44, s[2:3]
	v_cmp_ge_u32_e64 s[2:3], v14, v43
	v_addc_co_u32_e64 v44, vcc, 0, v44, vcc
	v_cmp_ge_u32_e32 vcc, v15, v43
	v_addc_co_u32_e64 v44, s[0:1], 0, v44, s[0:1]
	v_cmp_ge_u32_e64 s[0:1], v16, v43
	v_addc_co_u32_e64 v44, s[2:3], 0, v44, s[2:3]
	v_cmp_ge_u32_e64 s[2:3], v17, v43
	v_addc_co_u32_e64 v44, vcc, 0, v44, vcc
	v_cmp_ge_u32_e32 vcc, v18, v43
	v_addc_co_u32_e64 v44, s[0:1], 0, v44, s[0:1]
	v_cmp_ge_u32_e64 s[0:1], v19, v43
	v_addc_co_u32_e64 v44, s[2:3], 0, v44, s[2:3]
	v_cmp_ge_u32_e64 s[2:3], v20, v43
	v_addc_co_u32_e64 v44, vcc, 0, v44, vcc
	v_cmp_ge_u32_e32 vcc, v21, v43
	v_addc_co_u32_e64 v44, s[0:1], 0, v44, s[0:1]
	v_cmp_ge_u32_e64 s[0:1], v22, v43
	v_addc_co_u32_e64 v44, s[2:3], 0, v44, s[2:3]
	v_cmp_ge_u32_e64 s[2:3], v23, v43
	v_addc_co_u32_e64 v44, vcc, 0, v44, vcc
	v_cmp_ge_u32_e32 vcc, v24, v43
	v_addc_co_u32_e64 v44, s[0:1], 0, v44, s[0:1]
	v_cmp_ge_u32_e64 s[0:1], v25, v43
	v_addc_co_u32_e64 v44, s[2:3], 0, v44, s[2:3]
	v_cmp_ge_u32_e64 s[2:3], v26, v43
	v_addc_co_u32_e64 v44, vcc, 0, v44, vcc
	v_cmp_ge_u32_e32 vcc, v27, v43
	v_addc_co_u32_e64 v44, s[0:1], 0, v44, s[0:1]
	v_cmp_ge_u32_e64 s[0:1], v28, v43
	v_addc_co_u32_e64 v44, s[2:3], 0, v44, s[2:3]
	v_cmp_ge_u32_e64 s[2:3], v29, v43
	v_addc_co_u32_e64 v44, vcc, 0, v44, vcc
	v_cmp_ge_u32_e32 vcc, v30, v43
	v_addc_co_u32_e64 v44, s[0:1], 0, v44, s[0:1]
	v_cmp_ge_u32_e64 s[0:1], v31, v43
	v_addc_co_u32_e64 v44, s[2:3], 0, v44, s[2:3]
	v_addc_co_u32_e64 v44, vcc, 0, v44, vcc
	v_addc_co_u32_e64 v44, s[0:1], 0, v44, s[0:1]
	v_mov_b32_e32 v45, v44
	s_nop 1
	v_add_u32_dpp v45, v45, v45 row_ror:1 row_mask:0xf bank_mask:0xf
	s_nop 1
	v_add_u32_dpp v45, v45, v45 row_ror:2 row_mask:0xf bank_mask:0xf
	s_nop 1
	v_add_u32_dpp v45, v45, v45 row_ror:4 row_mask:0xf bank_mask:0xf
	s_nop 1
	v_add_u32_dpp v45, v45, v45 row_ror:8 row_mask:0xf bank_mask:0xf
	s_nop 0
	v_cmp_le_u32_e32 vcc, 0x100, v45
	s_nop 1
	v_cndmask_b32_e32 v36, v36, v42, vcc
	v_cndmask_b32_e32 v46, v46, v45, vcc
	v_cndmask_b32_e32 v47, v47, v44, vcc
	v_or_b32_e32 v42, 1, v36
	v_lshlrev_b32_e32 v41, v39, v42
	v_add_u32_e64 v43, v34, v41 clamp
	v_mov_b32_e32 v44, 0
	v_cmp_ge_u32_e32 vcc, v0, v43
	v_cmp_ge_u32_e64 s[0:1], v1, v43
	v_cmp_ge_u32_e64 s[2:3], v2, v43
	v_addc_co_u32_e64 v44, vcc, 0, v44, vcc
	v_cmp_ge_u32_e32 vcc, v3, v43
	v_addc_co_u32_e64 v44, s[0:1], 0, v44, s[0:1]
	v_cmp_ge_u32_e64 s[0:1], v4, v43
	v_addc_co_u32_e64 v44, s[2:3], 0, v44, s[2:3]
	v_cmp_ge_u32_e64 s[2:3], v5, v43
	v_addc_co_u32_e64 v44, vcc, 0, v44, vcc
	v_cmp_ge_u32_e32 vcc, v6, v43
	v_addc_co_u32_e64 v44, s[0:1], 0, v44, s[0:1]
	v_cmp_ge_u32_e64 s[0:1], v7, v43
	v_addc_co_u32_e64 v44, s[2:3], 0, v44, s[2:3]
	v_cmp_ge_u32_e64 s[2:3], v8, v43
	v_addc_co_u32_e64 v44, vcc, 0, v44, vcc
	v_cmp_ge_u32_e32 vcc, v9, v43
	v_addc_co_u32_e64 v44, s[0:1], 0, v44, s[0:1]
	v_cmp_ge_u32_e64 s[0:1], v10, v43
	v_addc_co_u32_e64 v44, s[2:3], 0, v44, s[2:3]
	v_cmp_ge_u32_e64 s[2:3], v11, v43
	v_addc_co_u32_e64 v44, vcc, 0, v44, vcc
	v_cmp_ge_u32_e32 vcc, v12, v43
	v_addc_co_u32_e64 v44, s[0:1], 0, v44, s[0:1]
	v_cmp_ge_u32_e64 s[0:1], v13, v43
	v_addc_co_u32_e64 v44, s[2:3], 0, v44, s[2:3]
	v_cmp_ge_u32_e64 s[2:3], v14, v43
	v_addc_co_u32_e64 v44, vcc, 0, v44, vcc
	v_cmp_ge_u32_e32 vcc, v15, v43
	v_addc_co_u32_e64 v44, s[0:1], 0, v44, s[0:1]
	v_cmp_ge_u32_e64 s[0:1], v16, v43
	v_addc_co_u32_e64 v44, s[2:3], 0, v44, s[2:3]
	v_cmp_ge_u32_e64 s[2:3], v17, v43
	v_addc_co_u32_e64 v44, vcc, 0, v44, vcc
	v_cmp_ge_u32_e32 vcc, v18, v43
	v_addc_co_u32_e64 v44, s[0:1], 0, v44, s[0:1]
	v_cmp_ge_u32_e64 s[0:1], v19, v43
	v_addc_co_u32_e64 v44, s[2:3], 0, v44, s[2:3]
	v_cmp_ge_u32_e64 s[2:3], v20, v43
	v_addc_co_u32_e64 v44, vcc, 0, v44, vcc
	v_cmp_ge_u32_e32 vcc, v21, v43
	v_addc_co_u32_e64 v44, s[0:1], 0, v44, s[0:1]
	v_cmp_ge_u32_e64 s[0:1], v22, v43
	v_addc_co_u32_e64 v44, s[2:3], 0, v44, s[2:3]
	v_cmp_ge_u32_e64 s[2:3], v23, v43
	v_addc_co_u32_e64 v44, vcc, 0, v44, vcc
	v_cmp_ge_u32_e32 vcc, v24, v43
	v_addc_co_u32_e64 v44, s[0:1], 0, v44, s[0:1]
	v_cmp_ge_u32_e64 s[0:1], v25, v43
	v_addc_co_u32_e64 v44, s[2:3], 0, v44, s[2:3]
	v_cmp_ge_u32_e64 s[2:3], v26, v43
	v_addc_co_u32_e64 v44, vcc, 0, v44, vcc
	v_cmp_ge_u32_e32 vcc, v27, v43
	v_addc_co_u32_e64 v44, s[0:1], 0, v44, s[0:1]
	v_cmp_ge_u32_e64 s[0:1], v28, v43
	v_addc_co_u32_e64 v44, s[2:3], 0, v44, s[2:3]
	v_cmp_ge_u32_e64 s[2:3], v29, v43
	v_addc_co_u32_e64 v44, vcc, 0, v44, vcc
	v_cmp_ge_u32_e32 vcc, v30, v43
	v_addc_co_u32_e64 v44, s[0:1], 0, v44, s[0:1]
	v_cmp_ge_u32_e64 s[0:1], v31, v43
	v_addc_co_u32_e64 v44, s[2:3], 0, v44, s[2:3]
	v_addc_co_u32_e64 v44, vcc, 0, v44, vcc
	v_addc_co_u32_e64 v44, s[0:1], 0, v44, s[0:1]
	v_mov_b32_e32 v45, v44
	s_nop 1
	v_add_u32_dpp v45, v45, v45 row_ror:1 row_mask:0xf bank_mask:0xf
	s_nop 1
	v_add_u32_dpp v45, v45, v45 row_ror:2 row_mask:0xf bank_mask:0xf
	s_nop 1
	v_add_u32_dpp v45, v45, v45 row_ror:4 row_mask:0xf bank_mask:0xf
	s_nop 1
	v_add_u32_dpp v45, v45, v45 row_ror:8 row_mask:0xf bank_mask:0xf
	s_nop 0
	v_cmp_le_u32_e32 vcc, 0x100, v45
	s_nop 1
	v_cndmask_b32_e32 v36, v36, v42, vcc
	v_cndmask_b32_e32 v46, v46, v45, vcc
	v_cndmask_b32_e32 v47, v47, v44, vcc
	v_lshlrev_b32_e32 v41, v39, v36
	v_add_u32_e32 v41, v34, v41
	v_cmp_ge_u32_e32 vcc, 0x140, v46
	v_cmp_eq_u32_e64 s[0:1], 0, v39
	v_lshlrev_b32_e32 v42, v39, v200
	v_add_u32_e32 v42, -1, v42
	s_or_b64 vcc, vcc, s[0:1]
	s_andn2_b64 s[0:1], vcc, s[50:51]
	s_nor_b64 s[2:3], vcc, s[50:51]
	s_or_b64 s[50:51], s[50:51], vcc
	v_add_u32_e64 v42, v41, v42 clamp
	v_min_u32_e32 v42, v42, v35
	v_cndmask_b32_e64 v37, v37, v41, s[0:1]
	v_cndmask_b32_e64 v62, v62, v47, s[0:1]
	v_cndmask_b32_e64 v35, v35, v42, s[2:3]
	v_cndmask_b32_e64 v34, v34, v41, s[2:3]
	s_cmp_eq_u64 s[50:51], -1
	s_cbranch_scc0 .Lp2apr0_iter
	s_mov_b64 exec, s[22:23]
	v_mov_b32_e32 v61, v62
	s_nop 1
	v_add_u32_dpp v61, v61, v61 row_shr:1 row_mask:0xf bank_mask:0xf bound_ctrl:1
	s_nop 1
	v_add_u32_dpp v61, v61, v61 row_shr:2 row_mask:0xf bank_mask:0xf bound_ctrl:1
	s_nop 1
	v_add_u32_dpp v61, v61, v61 row_shr:4 row_mask:0xf bank_mask:0xf bound_ctrl:1
	s_nop 1
	v_add_u32_dpp v61, v61, v61 row_shr:8 row_mask:0xf bank_mask:0xf bound_ctrl:1
	v_sub_u32_e32 v62, v61, v62
	v_lshl_add_u32 v41, v62, 2, v59
	v_cmpx_ge_u32_e32 vcc, v0, v37
	ds_write_b32 v41, v0
	v_add_u32_e32 v62, 1, v62
	s_mov_b64 exec, s[22:23]
	v_lshl_add_u32 v41, v62, 2, v59
	v_cmpx_ge_u32_e32 vcc, v1, v37
	ds_write_b32 v41, v1
	v_add_u32_e32 v62, 1, v62
	s_mov_b64 exec, s[22:23]
	v_lshl_add_u32 v41, v62, 2, v59
	v_cmpx_ge_u32_e32 vcc, v2, v37
	ds_write_b32 v41, v2
	v_add_u32_e32 v62, 1, v62
	s_mov_b64 exec, s[22:23]
	v_lshl_add_u32 v41, v62, 2, v59
	v_cmpx_ge_u32_e32 vcc, v3, v37
	ds_write_b32 v41, v3
	v_add_u32_e32 v62, 1, v62
	s_mov_b64 exec, s[22:23]
	v_lshl_add_u32 v41, v62, 2, v59
	v_cmpx_ge_u32_e32 vcc, v4, v37
	ds_write_b32 v41, v4
	v_add_u32_e32 v62, 1, v62
	s_mov_b64 exec, s[22:23]
	v_lshl_add_u32 v41, v62, 2, v59
	v_cmpx_ge_u32_e32 vcc, v5, v37
	ds_write_b32 v41, v5
	v_add_u32_e32 v62, 1, v62
	s_mov_b64 exec, s[22:23]
	v_lshl_add_u32 v41, v62, 2, v59
	v_cmpx_ge_u32_e32 vcc, v6, v37
	ds_write_b32 v41, v6
	v_add_u32_e32 v62, 1, v62
	s_mov_b64 exec, s[22:23]
	v_lshl_add_u32 v41, v62, 2, v59
	v_cmpx_ge_u32_e32 vcc, v7, v37
	ds_write_b32 v41, v7
	v_add_u32_e32 v62, 1, v62
	s_mov_b64 exec, s[22:23]
	v_lshl_add_u32 v41, v62, 2, v59
	v_cmpx_ge_u32_e32 vcc, v8, v37
	ds_write_b32 v41, v8
	v_add_u32_e32 v62, 1, v62
	s_mov_b64 exec, s[22:23]
	v_lshl_add_u32 v41, v62, 2, v59
	v_cmpx_ge_u32_e32 vcc, v9, v37
	ds_write_b32 v41, v9
	v_add_u32_e32 v62, 1, v62
	s_mov_b64 exec, s[22:23]
	v_lshl_add_u32 v41, v62, 2, v59
	v_cmpx_ge_u32_e32 vcc, v10, v37
	ds_write_b32 v41, v10
	v_add_u32_e32 v62, 1, v62
	s_mov_b64 exec, s[22:23]
	v_lshl_add_u32 v41, v62, 2, v59
	v_cmpx_ge_u32_e32 vcc, v11, v37
	ds_write_b32 v41, v11
	v_add_u32_e32 v62, 1, v62
	s_mov_b64 exec, s[22:23]
	v_lshl_add_u32 v41, v62, 2, v59
	v_cmpx_ge_u32_e32 vcc, v12, v37
	ds_write_b32 v41, v12
	v_add_u32_e32 v62, 1, v62
	s_mov_b64 exec, s[22:23]
	v_lshl_add_u32 v41, v62, 2, v59
	v_cmpx_ge_u32_e32 vcc, v13, v37
	ds_write_b32 v41, v13
	v_add_u32_e32 v62, 1, v62
	s_mov_b64 exec, s[22:23]
	v_lshl_add_u32 v41, v62, 2, v59
	v_cmpx_ge_u32_e32 vcc, v14, v37
	ds_write_b32 v41, v14
	v_add_u32_e32 v62, 1, v62
	s_mov_b64 exec, s[22:23]
	v_lshl_add_u32 v41, v62, 2, v59
	v_cmpx_ge_u32_e32 vcc, v15, v37
	ds_write_b32 v41, v15
	v_add_u32_e32 v62, 1, v62
	s_mov_b64 exec, s[22:23]
	v_lshl_add_u32 v41, v62, 2, v59
	v_cmpx_ge_u32_e32 vcc, v16, v37
	ds_write_b32 v41, v16
	v_add_u32_e32 v62, 1, v62
	s_mov_b64 exec, s[22:23]
	v_lshl_add_u32 v41, v62, 2, v59
	v_cmpx_ge_u32_e32 vcc, v17, v37
	ds_write_b32 v41, v17
	v_add_u32_e32 v62, 1, v62
	s_mov_b64 exec, s[22:23]
	v_lshl_add_u32 v41, v62, 2, v59
	v_cmpx_ge_u32_e32 vcc, v18, v37
	ds_write_b32 v41, v18
	v_add_u32_e32 v62, 1, v62
	s_mov_b64 exec, s[22:23]
	v_lshl_add_u32 v41, v62, 2, v59
	v_cmpx_ge_u32_e32 vcc, v19, v37
	ds_write_b32 v41, v19
	v_add_u32_e32 v62, 1, v62
	s_mov_b64 exec, s[22:23]
	v_lshl_add_u32 v41, v62, 2, v59
	v_cmpx_ge_u32_e32 vcc, v20, v37
	ds_write_b32 v41, v20
	v_add_u32_e32 v62, 1, v62
	s_mov_b64 exec, s[22:23]
	v_lshl_add_u32 v41, v62, 2, v59
	v_cmpx_ge_u32_e32 vcc, v21, v37
	ds_write_b32 v41, v21
	v_add_u32_e32 v62, 1, v62
	s_mov_b64 exec, s[22:23]
	v_lshl_add_u32 v41, v62, 2, v59
	v_cmpx_ge_u32_e32 vcc, v22, v37
	ds_write_b32 v41, v22
	v_add_u32_e32 v62, 1, v62
	s_mov_b64 exec, s[22:23]
	v_lshl_add_u32 v41, v62, 2, v59
	v_cmpx_ge_u32_e32 vcc, v23, v37
	ds_write_b32 v41, v23
	v_add_u32_e32 v62, 1, v62
	s_mov_b64 exec, s[22:23]
	v_lshl_add_u32 v41, v62, 2, v59
	v_cmpx_ge_u32_e32 vcc, v24, v37
	ds_write_b32 v41, v24
	v_add_u32_e32 v62, 1, v62
	s_mov_b64 exec, s[22:23]
	v_lshl_add_u32 v41, v62, 2, v59
	v_cmpx_ge_u32_e32 vcc, v25, v37
	ds_write_b32 v41, v25
	v_add_u32_e32 v62, 1, v62
	s_mov_b64 exec, s[22:23]
	v_lshl_add_u32 v41, v62, 2, v59
	v_cmpx_ge_u32_e32 vcc, v26, v37
	ds_write_b32 v41, v26
	v_add_u32_e32 v62, 1, v62
	s_mov_b64 exec, s[22:23]
	v_lshl_add_u32 v41, v62, 2, v59
	v_cmpx_ge_u32_e32 vcc, v27, v37
	ds_write_b32 v41, v27
	v_add_u32_e32 v62, 1, v62
	s_mov_b64 exec, s[22:23]
	v_lshl_add_u32 v41, v62, 2, v59
	v_cmpx_ge_u32_e32 vcc, v28, v37
	ds_write_b32 v41, v28
	v_add_u32_e32 v62, 1, v62
	s_mov_b64 exec, s[22:23]
	v_lshl_add_u32 v41, v62, 2, v59
	v_cmpx_ge_u32_e32 vcc, v29, v37
	ds_write_b32 v41, v29
	v_add_u32_e32 v62, 1, v62
	s_mov_b64 exec, s[22:23]
	v_lshl_add_u32 v41, v62, 2, v59
	v_cmpx_ge_u32_e32 vcc, v30, v37
	ds_write_b32 v41, v30
	v_add_u32_e32 v62, 1, v62
	s_mov_b64 exec, s[22:23]
	v_lshl_add_u32 v41, v62, 2, v59
	v_cmpx_ge_u32_e32 vcc, v31, v37
	ds_write_b32 v41, v31
	v_add_u32_e32 v62, 1, v62
	s_mov_b64 exec, s[22:23]
	s_mov_b64 exec, -1
	v_and_b32_e32 v41, 0xffffe000, v37
	v_ashrrev_i32_e32 v42, 31, v41
	v_not_b32_e32 v42, v42
	v_or_b32_e32 v42, 0x80000000, v42
	v_xor_b32_e32 v63, v41, v42
	s_cmpk_lt_i32 s78, 0x141
	s_cbranch_scc1 .Lp2apr0_o0
	v_readlane_b32 s0, v63, 0
	v_readlane_b32 s73, v37, 0
	v_readlane_b32 s78, v61, 15
	v_mov_b32_e32 v231, s0

.Lp2apr1_iter:
	v_sub_u32_e32 v38, v35, v34
	v_or_b32_e32 v41, 1, v38
	v_ffbh_u32_e32 v41, v41
	v_sub_u32_e32 v41, 26, v41
	v_max_i32_e32 v39, 0, v41
	v_mov_b32_e32 v36, 0
	v_or_b32_e32 v42, 32, v36
	v_lshlrev_b32_e32 v41, v39, v42
	v_add_u32_e64 v43, v34, v41 clamp
	v_mov_b32_e32 v44, 0
	v_cmp_ge_u32_e32 vcc, v0, v43
	v_cmp_ge_u32_e64 s[0:1], v1, v43
	v_cmp_ge_u32_e64 s[2:3], v2, v43
	v_addc_co_u32_e64 v44, vcc, 0, v44, vcc
	v_cmp_ge_u32_e32 vcc, v3, v43
	v_addc_co_u32_e64 v44, s[0:1], 0, v44, s[0:1]
	v_cmp_ge_u32_e64 s[0:1], v4, v43
	v_addc_co_u32_e64 v44, s[2:3], 0, v44, s[2:3]
	v_cmp_ge_u32_e64 s[2:3], v5, v43
	v_addc_co_u32_e64 v44, vcc, 0, v44, vcc
	v_cmp_ge_u32_e32 vcc, v6, v43
	v_addc_co_u32_e64 v44, s[0:1], 0, v44, s[0:1]
	v_cmp_ge_u32_e64 s[0:1], v7, v43
	v_addc_co_u32_e64 v44, s[2:3], 0, v44, s[2:3]
	v_cmp_ge_u32_e64 s[2:3], v8, v43
	v_addc_co_u32_e64 v44, vcc, 0, v44, vcc
	v_cmp_ge_u32_e32 vcc, v9, v43
	v_addc_co_u32_e64 v44, s[0:1], 0, v44, s[0:1]
	v_cmp_ge_u32_e64 s[0:1], v10, v43
	v_addc_co_u32_e64 v44, s[2:3], 0, v44, s[2:3]
	v_cmp_ge_u32_e64 s[2:3], v11, v43
	v_addc_co_u32_e64 v44, vcc, 0, v44, vcc
	v_cmp_ge_u32_e32 vcc, v12, v43
	v_addc_co_u32_e64 v44, s[0:1], 0, v44, s[0:1]
	v_cmp_ge_u32_e64 s[0:1], v13, v43
	v_addc_co_u32_e64 v44, s[2:3], 0, v44, s[2:3]
	v_cmp_ge_u32_e64 s[2:3], v14, v43
	v_addc_co_u32_e64 v44, vcc, 0, v44, vcc
	v_cmp_ge_u32_e32 vcc, v15, v43
	v_addc_co_u32_e64 v44, s[0:1], 0, v44, s[0:1]
	v_cmp_ge_u32_e64 s[0:1], v16, v43
	v_addc_co_u32_e64 v44, s[2:3], 0, v44, s[2:3]
	v_cmp_ge_u32_e64 s[2:3], v17, v43
	v_addc_co_u32_e64 v44, vcc, 0, v44, vcc
	v_cmp_ge_u32_e32 vcc, v18, v43
	v_addc_co_u32_e64 v44, s[0:1], 0, v44, s[0:1]
	v_cmp_ge_u32_e64 s[0:1], v19, v43
	v_addc_co_u32_e64 v44, s[2:3], 0, v44, s[2:3]
	v_cmp_ge_u32_e64 s[2:3], v20, v43
	v_addc_co_u32_e64 v44, vcc, 0, v44, vcc
	v_cmp_ge_u32_e32 vcc, v21, v43
	v_addc_co_u32_e64 v44, s[0:1], 0, v44, s[0:1]
	v_cmp_ge_u32_e64 s[0:1], v22, v43
	v_addc_co_u32_e64 v44, s[2:3], 0, v44, s[2:3]
	v_cmp_ge_u32_e64 s[2:3], v23, v43
	v_addc_co_u32_e64 v44, vcc, 0, v44, vcc
	v_cmp_ge_u32_e32 vcc, v24, v43
	v_addc_co_u32_e64 v44, s[0:1], 0, v44, s[0:1]
	v_cmp_ge_u32_e64 s[0:1], v25, v43
	v_addc_co_u32_e64 v44, s[2:3], 0, v44, s[2:3]
	v_cmp_ge_u32_e64 s[2:3], v26, v43
	v_addc_co_u32_e64 v44, vcc, 0, v44, vcc
	v_cmp_ge_u32_e32 vcc, v27, v43
	v_addc_co_u32_e64 v44, s[0:1], 0, v44, s[0:1]
	v_cmp_ge_u32_e64 s[0:1], v28, v43
	v_addc_co_u32_e64 v44, s[2:3], 0, v44, s[2:3]
	v_cmp_ge_u32_e64 s[2:3], v29, v43
	v_addc_co_u32_e64 v44, vcc, 0, v44, vcc
	v_cmp_ge_u32_e32 vcc, v30, v43
	v_addc_co_u32_e64 v44, s[0:1], 0, v44, s[0:1]
	v_cmp_ge_u32_e64 s[0:1], v31, v43
	v_addc_co_u32_e64 v44, s[2:3], 0, v44, s[2:3]
	v_addc_co_u32_e64 v44, vcc, 0, v44, vcc
	v_addc_co_u32_e64 v44, s[0:1], 0, v44, s[0:1]
	v_mov_b32_e32 v45, v44
	s_nop 1
	v_add_u32_dpp v45, v45, v45 row_ror:1 row_mask:0xf bank_mask:0xf
	s_nop 1
	v_add_u32_dpp v45, v45, v45 row_ror:2 row_mask:0xf bank_mask:0xf
	s_nop 1
	v_add_u32_dpp v45, v45, v45 row_ror:4 row_mask:0xf bank_mask:0xf
	s_nop 1
	v_add_u32_dpp v45, v45, v45 row_ror:8 row_mask:0xf bank_mask:0xf
	s_nop 0
	v_cmp_le_u32_e32 vcc, 0x100, v45
	s_nop 1
	v_cndmask_b32_e32 v36, v36, v42, vcc
	v_cndmask_b32_e32 v46, v46, v45, vcc
	v_cndmask_b32_e32 v47, v47, v44, vcc
	v_or_b32_e32 v42, 16, v36
	v_lshlrev_b32_e32 v41, v39, v42
	v_add_u32_e64 v43, v34, v41 clamp
	v_mov_b32_e32 v44, 0
	v_cmp_ge_u32_e32 vcc, v0, v43
	v_cmp_ge_u32_e64 s[0:1], v1, v43
	v_cmp_ge_u32_e64 s[2:3], v2, v43
	v_addc_co_u32_e64 v44, vcc, 0, v44, vcc
	v_cmp_ge_u32_e32 vcc, v3, v43
	v_addc_co_u32_e64 v44, s[0:1], 0, v44, s[0:1]
	v_cmp_ge_u32_e64 s[0:1], v4, v43
	v_addc_co_u32_e64 v44, s[2:3], 0, v44, s[2:3]
	v_cmp_ge_u32_e64 s[2:3], v5, v43
	v_addc_co_u32_e64 v44, vcc, 0, v44, vcc
	v_cmp_ge_u32_e32 vcc, v6, v43
	v_addc_co_u32_e64 v44, s[0:1], 0, v44, s[0:1]
	v_cmp_ge_u32_e64 s[0:1], v7, v43
	v_addc_co_u32_e64 v44, s[2:3], 0, v44, s[2:3]
	v_cmp_ge_u32_e64 s[2:3], v8, v43
	v_addc_co_u32_e64 v44, vcc, 0, v44, vcc
	v_cmp_ge_u32_e32 vcc, v9, v43
	v_addc_co_u32_e64 v44, s[0:1], 0, v44, s[0:1]
	v_cmp_ge_u32_e64 s[0:1], v10, v43
	v_addc_co_u32_e64 v44, s[2:3], 0, v44, s[2:3]
	v_cmp_ge_u32_e64 s[2:3], v11, v43
	v_addc_co_u32_e64 v44, vcc, 0, v44, vcc
	v_cmp_ge_u32_e32 vcc, v12, v43
	v_addc_co_u32_e64 v44, s[0:1], 0, v44, s[0:1]
	v_cmp_ge_u32_e64 s[0:1], v13, v43
	v_addc_co_u32_e64 v44, s[2:3], 0, v44, s[2:3]
	v_cmp_ge_u32_e64 s[2:3], v14, v43
	v_addc_co_u32_e64 v44, vcc, 0, v44, vcc
	v_cmp_ge_u32_e32 vcc, v15, v43
	v_addc_co_u32_e64 v44, s[0:1], 0, v44, s[0:1]
	v_cmp_ge_u32_e64 s[0:1], v16, v43
	v_addc_co_u32_e64 v44, s[2:3], 0, v44, s[2:3]
	v_cmp_ge_u32_e64 s[2:3], v17, v43
	v_addc_co_u32_e64 v44, vcc, 0, v44, vcc
	v_cmp_ge_u32_e32 vcc, v18, v43
	v_addc_co_u32_e64 v44, s[0:1], 0, v44, s[0:1]
	v_cmp_ge_u32_e64 s[0:1], v19, v43
	v_addc_co_u32_e64 v44, s[2:3], 0, v44, s[2:3]
	v_cmp_ge_u32_e64 s[2:3], v20, v43
	v_addc_co_u32_e64 v44, vcc, 0, v44, vcc
	v_cmp_ge_u32_e32 vcc, v21, v43
	v_addc_co_u32_e64 v44, s[0:1], 0, v44, s[0:1]
	v_cmp_ge_u32_e64 s[0:1], v22, v43
	v_addc_co_u32_e64 v44, s[2:3], 0, v44, s[2:3]
	v_cmp_ge_u32_e64 s[2:3], v23, v43
	v_addc_co_u32_e64 v44, vcc, 0, v44, vcc
	v_cmp_ge_u32_e32 vcc, v24, v43
	v_addc_co_u32_e64 v44, s[0:1], 0, v44, s[0:1]
	v_cmp_ge_u32_e64 s[0:1], v25, v43
	v_addc_co_u32_e64 v44, s[2:3], 0, v44, s[2:3]
	v_cmp_ge_u32_e64 s[2:3], v26, v43
	v_addc_co_u32_e64 v44, vcc, 0, v44, vcc
	v_cmp_ge_u32_e32 vcc, v27, v43
	v_addc_co_u32_e64 v44, s[0:1], 0, v44, s[0:1]
	v_cmp_ge_u32_e64 s[0:1], v28, v43
	v_addc_co_u32_e64 v44, s[2:3], 0, v44, s[2:3]
	v_cmp_ge_u32_e64 s[2:3], v29, v43
	v_addc_co_u32_e64 v44, vcc, 0, v44, vcc
	v_cmp_ge_u32_e32 vcc, v30, v43
	v_addc_co_u32_e64 v44, s[0:1], 0, v44, s[0:1]
	v_cmp_ge_u32_e64 s[0:1], v31, v43
	v_addc_co_u32_e64 v44, s[2:3], 0, v44, s[2:3]
	v_addc_co_u32_e64 v44, vcc, 0, v44, vcc
	v_addc_co_u32_e64 v44, s[0:1], 0, v44, s[0:1]
	v_mov_b32_e32 v45, v44
	s_nop 1
	v_add_u32_dpp v45, v45, v45 row_ror:1 row_mask:0xf bank_mask:0xf
	s_nop 1
	v_add_u32_dpp v45, v45, v45 row_ror:2 row_mask:0xf bank_mask:0xf
	s_nop 1
	v_add_u32_dpp v45, v45, v45 row_ror:4 row_mask:0xf bank_mask:0xf
	s_nop 1
	v_add_u32_dpp v45, v45, v45 row_ror:8 row_mask:0xf bank_mask:0xf
	s_nop 0
	v_cmp_le_u32_e32 vcc, 0x100, v45
	s_nop 1
	v_cndmask_b32_e32 v36, v36, v42, vcc
	v_cndmask_b32_e32 v46, v46, v45, vcc
	v_cndmask_b32_e32 v47, v47, v44, vcc
	v_or_b32_e32 v42, 8, v36
	v_lshlrev_b32_e32 v41, v39, v42
	v_add_u32_e64 v43, v34, v41 clamp
	v_mov_b32_e32 v44, 0
	v_cmp_ge_u32_e32 vcc, v0, v43
	v_cmp_ge_u32_e64 s[0:1], v1, v43
	v_cmp_ge_u32_e64 s[2:3], v2, v43
	v_addc_co_u32_e64 v44, vcc, 0, v44, vcc
	v_cmp_ge_u32_e32 vcc, v3, v43
	v_addc_co_u32_e64 v44, s[0:1], 0, v44, s[0:1]
	v_cmp_ge_u32_e64 s[0:1], v4, v43
	v_addc_co_u32_e64 v44, s[2:3], 0, v44, s[2:3]
	v_cmp_ge_u32_e64 s[2:3], v5, v43
	v_addc_co_u32_e64 v44, vcc, 0, v44, vcc
	v_cmp_ge_u32_e32 vcc, v6, v43
	v_addc_co_u32_e64 v44, s[0:1], 0, v44, s[0:1]
	v_cmp_ge_u32_e64 s[0:1], v7, v43
	v_addc_co_u32_e64 v44, s[2:3], 0, v44, s[2:3]
	v_cmp_ge_u32_e64 s[2:3], v8, v43
	v_addc_co_u32_e64 v44, vcc, 0, v44, vcc
	v_cmp_ge_u32_e32 vcc, v9, v43
	v_addc_co_u32_e64 v44, s[0:1], 0, v44, s[0:1]
	v_cmp_ge_u32_e64 s[0:1], v10, v43
	v_addc_co_u32_e64 v44, s[2:3], 0, v44, s[2:3]
	v_cmp_ge_u32_e64 s[2:3], v11, v43
	v_addc_co_u32_e64 v44, vcc, 0, v44, vcc
	v_cmp_ge_u32_e32 vcc, v12, v43
	v_addc_co_u32_e64 v44, s[0:1], 0, v44, s[0:1]
	v_cmp_ge_u32_e64 s[0:1], v13, v43
	v_addc_co_u32_e64 v44, s[2:3], 0, v44, s[2:3]
	v_cmp_ge_u32_e64 s[2:3], v14, v43
	v_addc_co_u32_e64 v44, vcc, 0, v44, vcc
	v_cmp_ge_u32_e32 vcc, v15, v43
	v_addc_co_u32_e64 v44, s[0:1], 0, v44, s[0:1]
	v_cmp_ge_u32_e64 s[0:1], v16, v43
	v_addc_co_u32_e64 v44, s[2:3], 0, v44, s[2:3]
	v_cmp_ge_u32_e64 s[2:3], v17, v43
	v_addc_co_u32_e64 v44, vcc, 0, v44, vcc
	v_cmp_ge_u32_e32 vcc, v18, v43
	v_addc_co_u32_e64 v44, s[0:1], 0, v44, s[0:1]
	v_cmp_ge_u32_e64 s[0:1], v19, v43
	v_addc_co_u32_e64 v44, s[2:3], 0, v44, s[2:3]
	v_cmp_ge_u32_e64 s[2:3], v20, v43
	v_addc_co_u32_e64 v44, vcc, 0, v44, vcc
	v_cmp_ge_u32_e32 vcc, v21, v43
	v_addc_co_u32_e64 v44, s[0:1], 0, v44, s[0:1]
	v_cmp_ge_u32_e64 s[0:1], v22, v43
	v_addc_co_u32_e64 v44, s[2:3], 0, v44, s[2:3]
	v_cmp_ge_u32_e64 s[2:3], v23, v43
	v_addc_co_u32_e64 v44, vcc, 0, v44, vcc
	v_cmp_ge_u32_e32 vcc, v24, v43
	v_addc_co_u32_e64 v44, s[0:1], 0, v44, s[0:1]
	v_cmp_ge_u32_e64 s[0:1], v25, v43
	v_addc_co_u32_e64 v44, s[2:3], 0, v44, s[2:3]
	v_cmp_ge_u32_e64 s[2:3], v26, v43
	v_addc_co_u32_e64 v44, vcc, 0, v44, vcc
	v_cmp_ge_u32_e32 vcc, v27, v43
	v_addc_co_u32_e64 v44, s[0:1], 0, v44, s[0:1]
	v_cmp_ge_u32_e64 s[0:1], v28, v43
	v_addc_co_u32_e64 v44, s[2:3], 0, v44, s[2:3]
	v_cmp_ge_u32_e64 s[2:3], v29, v43
	v_addc_co_u32_e64 v44, vcc, 0, v44, vcc
	v_cmp_ge_u32_e32 vcc, v30, v43
	v_addc_co_u32_e64 v44, s[0:1], 0, v44, s[0:1]
	v_cmp_ge_u32_e64 s[0:1], v31, v43
	v_addc_co_u32_e64 v44, s[2:3], 0, v44, s[2:3]
	v_addc_co_u32_e64 v44, vcc, 0, v44, vcc
	v_addc_co_u32_e64 v44, s[0:1], 0, v44, s[0:1]
	v_mov_b32_e32 v45, v44
	s_nop 1
	v_add_u32_dpp v45, v45, v45 row_ror:1 row_mask:0xf bank_mask:0xf
	s_nop 1
	v_add_u32_dpp v45, v45, v45 row_ror:2 row_mask:0xf bank_mask:0xf
	s_nop 1
	v_add_u32_dpp v45, v45, v45 row_ror:4 row_mask:0xf bank_mask:0xf
	s_nop 1
	v_add_u32_dpp v45, v45, v45 row_ror:8 row_mask:0xf bank_mask:0xf
	s_nop 0
	v_cmp_le_u32_e32 vcc, 0x100, v45
	s_nop 1
	v_cndmask_b32_e32 v36, v36, v42, vcc
	v_cndmask_b32_e32 v46, v46, v45, vcc
	v_cndmask_b32_e32 v47, v47, v44, vcc
	v_or_b32_e32 v42, 4, v36
	v_lshlrev_b32_e32 v41, v39, v42
	v_add_u32_e64 v43, v34, v41 clamp
	v_mov_b32_e32 v44, 0
	v_cmp_ge_u32_e32 vcc, v0, v43
	v_cmp_ge_u32_e64 s[0:1], v1, v43
	v_cmp_ge_u32_e64 s[2:3], v2, v43
	v_addc_co_u32_e64 v44, vcc, 0, v44, vcc
	v_cmp_ge_u32_e32 vcc, v3, v43
	v_addc_co_u32_e64 v44, s[0:1], 0, v44, s[0:1]
	v_cmp_ge_u32_e64 s[0:1], v4, v43
	v_addc_co_u32_e64 v44, s[2:3], 0, v44, s[2:3]
	v_cmp_ge_u32_e64 s[2:3], v5, v43
	v_addc_co_u32_e64 v44, vcc, 0, v44, vcc
	v_cmp_ge_u32_e32 vcc, v6, v43
	v_addc_co_u32_e64 v44, s[0:1], 0, v44, s[0:1]
	v_cmp_ge_u32_e64 s[0:1], v7, v43
	v_addc_co_u32_e64 v44, s[2:3], 0, v44, s[2:3]
	v_cmp_ge_u32_e64 s[2:3], v8, v43
	v_addc_co_u32_e64 v44, vcc, 0, v44, vcc
	v_cmp_ge_u32_e32 vcc, v9, v43
	v_addc_co_u32_e64 v44, s[0:1], 0, v44, s[0:1]
	v_cmp_ge_u32_e64 s[0:1], v10, v43
	v_addc_co_u32_e64 v44, s[2:3], 0, v44, s[2:3]
	v_cmp_ge_u32_e64 s[2:3], v11, v43
	v_addc_co_u32_e64 v44, vcc, 0, v44, vcc
	v_cmp_ge_u32_e32 vcc, v12, v43
	v_addc_co_u32_e64 v44, s[0:1], 0, v44, s[0:1]
	v_cmp_ge_u32_e64 s[0:1], v13, v43
	v_addc_co_u32_e64 v44, s[2:3], 0, v44, s[2:3]
	v_cmp_ge_u32_e64 s[2:3], v14, v43
	v_addc_co_u32_e64 v44, vcc, 0, v44, vcc
	v_cmp_ge_u32_e32 vcc, v15, v43
	v_addc_co_u32_e64 v44, s[0:1], 0, v44, s[0:1]
	v_cmp_ge_u32_e64 s[0:1], v16, v43
	v_addc_co_u32_e64 v44, s[2:3], 0, v44, s[2:3]
	v_cmp_ge_u32_e64 s[2:3], v17, v43
	v_addc_co_u32_e64 v44, vcc, 0, v44, vcc
	v_cmp_ge_u32_e32 vcc, v18, v43
	v_addc_co_u32_e64 v44, s[0:1], 0, v44, s[0:1]
	v_cmp_ge_u32_e64 s[0:1], v19, v43
	v_addc_co_u32_e64 v44, s[2:3], 0, v44, s[2:3]
	v_cmp_ge_u32_e64 s[2:3], v20, v43
	v_addc_co_u32_e64 v44, vcc, 0, v44, vcc
	v_cmp_ge_u32_e32 vcc, v21, v43
	v_addc_co_u32_e64 v44, s[0:1], 0, v44, s[0:1]
	v_cmp_ge_u32_e64 s[0:1], v22, v43
	v_addc_co_u32_e64 v44, s[2:3], 0, v44, s[2:3]
	v_cmp_ge_u32_e64 s[2:3], v23, v43
	v_addc_co_u32_e64 v44, vcc, 0, v44, vcc
	v_cmp_ge_u32_e32 vcc, v24, v43
	v_addc_co_u32_e64 v44, s[0:1], 0, v44, s[0:1]
	v_cmp_ge_u32_e64 s[0:1], v25, v43
	v_addc_co_u32_e64 v44, s[2:3], 0, v44, s[2:3]
	v_cmp_ge_u32_e64 s[2:3], v26, v43
	v_addc_co_u32_e64 v44, vcc, 0, v44, vcc
	v_cmp_ge_u32_e32 vcc, v27, v43
	v_addc_co_u32_e64 v44, s[0:1], 0, v44, s[0:1]
	v_cmp_ge_u32_e64 s[0:1], v28, v43
	v_addc_co_u32_e64 v44, s[2:3], 0, v44, s[2:3]
	v_cmp_ge_u32_e64 s[2:3], v29, v43
	v_addc_co_u32_e64 v44, vcc, 0, v44, vcc
	v_cmp_ge_u32_e32 vcc, v30, v43
	v_addc_co_u32_e64 v44, s[0:1], 0, v44, s[0:1]
	v_cmp_ge_u32_e64 s[0:1], v31, v43
	v_addc_co_u32_e64 v44, s[2:3], 0, v44, s[2:3]
	v_addc_co_u32_e64 v44, vcc, 0, v44, vcc
	v_addc_co_u32_e64 v44, s[0:1], 0, v44, s[0:1]
	v_mov_b32_e32 v45, v44
	s_nop 1
	v_add_u32_dpp v45, v45, v45 row_ror:1 row_mask:0xf bank_mask:0xf
	s_nop 1
	v_add_u32_dpp v45, v45, v45 row_ror:2 row_mask:0xf bank_mask:0xf
	s_nop 1
	v_add_u32_dpp v45, v45, v45 row_ror:4 row_mask:0xf bank_mask:0xf
	s_nop 1
	v_add_u32_dpp v45, v45, v45 row_ror:8 row_mask:0xf bank_mask:0xf
	s_nop 0
	v_cmp_le_u32_e32 vcc, 0x100, v45
	s_nop 1
	v_cndmask_b32_e32 v36, v36, v42, vcc
	v_cndmask_b32_e32 v46, v46, v45, vcc
	v_cndmask_b32_e32 v47, v47, v44, vcc
	v_or_b32_e32 v42, 2, v36
	v_lshlrev_b32_e32 v41, v39, v42
	v_add_u32_e64 v43, v34, v41 clamp
	v_mov_b32_e32 v44, 0
	v_cmp_ge_u32_e32 vcc, v0, v43
	v_cmp_ge_u32_e64 s[0:1], v1, v43
	v_cmp_ge_u32_e64 s[2:3], v2, v43
	v_addc_co_u32_e64 v44, vcc, 0, v44, vcc
	v_cmp_ge_u32_e32 vcc, v3, v43
	v_addc_co_u32_e64 v44, s[0:1], 0, v44, s[0:1]
	v_cmp_ge_u32_e64 s[0:1], v4, v43
	v_addc_co_u32_e64 v44, s[2:3], 0, v44, s[2:3]
	v_cmp_ge_u32_e64 s[2:3], v5, v43
	v_addc_co_u32_e64 v44, vcc, 0, v44, vcc
	v_cmp_ge_u32_e32 vcc, v6, v43
	v_addc_co_u32_e64 v44, s[0:1], 0, v44, s[0:1]
	v_cmp_ge_u32_e64 s[0:1], v7, v43
	v_addc_co_u32_e64 v44, s[2:3], 0, v44, s[2:3]
	v_cmp_ge_u32_e64 s[2:3], v8, v43
	v_addc_co_u32_e64 v44, vcc, 0, v44, vcc
	v_cmp_ge_u32_e32 vcc, v9, v43
	v_addc_co_u32_e64 v44, s[0:1], 0, v44, s[0:1]
	v_cmp_ge_u32_e64 s[0:1], v10, v43
	v_addc_co_u32_e64 v44, s[2:3], 0, v44, s[2:3]
	v_cmp_ge_u32_e64 s[2:3], v11, v43
	v_addc_co_u32_e64 v44, vcc, 0, v44, vcc
	v_cmp_ge_u32_e32 vcc, v12, v43
	v_addc_co_u32_e64 v44, s[0:1], 0, v44, s[0:1]
	v_cmp_ge_u32_e64 s[0:1], v13, v43
	v_addc_co_u32_e64 v44, s[2:3], 0, v44, s[2:3]
	v_cmp_ge_u32_e64 s[2:3], v14, v43
	v_addc_co_u32_e64 v44, vcc, 0, v44, vcc
	v_cmp_ge_u32_e32 vcc, v15, v43
	v_addc_co_u32_e64 v44, s[0:1], 0, v44, s[0:1]
	v_cmp_ge_u32_e64 s[0:1], v16, v43
	v_addc_co_u32_e64 v44, s[2:3], 0, v44, s[2:3]
	v_cmp_ge_u32_e64 s[2:3], v17, v43
	v_addc_co_u32_e64 v44, vcc, 0, v44, vcc
	v_cmp_ge_u32_e32 vcc, v18, v43
	v_addc_co_u32_e64 v44, s[0:1], 0, v44, s[0:1]
	v_cmp_ge_u32_e64 s[0:1], v19, v43
	v_addc_co_u32_e64 v44, s[2:3], 0, v44, s[2:3]
	v_cmp_ge_u32_e64 s[2:3], v20, v43
	v_addc_co_u32_e64 v44, vcc, 0, v44, vcc
	v_cmp_ge_u32_e32 vcc, v21, v43
	v_addc_co_u32_e64 v44, s[0:1], 0, v44, s[0:1]
	v_cmp_ge_u32_e64 s[0:1], v22, v43
	v_addc_co_u32_e64 v44, s[2:3], 0, v44, s[2:3]
	v_cmp_ge_u32_e64 s[2:3], v23, v43
	v_addc_co_u32_e64 v44, vcc, 0, v44, vcc
	v_cmp_ge_u32_e32 vcc, v24, v43
	v_addc_co_u32_e64 v44, s[0:1], 0, v44, s[0:1]
	v_cmp_ge_u32_e64 s[0:1], v25, v43
	v_addc_co_u32_e64 v44, s[2:3], 0, v44, s[2:3]
	v_cmp_ge_u32_e64 s[2:3], v26, v43
	v_addc_co_u32_e64 v44, vcc, 0, v44, vcc
	v_cmp_ge_u32_e32 vcc, v27, v43
	v_addc_co_u32_e64 v44, s[0:1], 0, v44, s[0:1]
	v_cmp_ge_u32_e64 s[0:1], v28, v43
	v_addc_co_u32_e64 v44, s[2:3], 0, v44, s[2:3]
	v_cmp_ge_u32_e64 s[2:3], v29, v43
	v_addc_co_u32_e64 v44, vcc, 0, v44, vcc
	v_cmp_ge_u32_e32 vcc, v30, v43
	v_addc_co_u32_e64 v44, s[0:1], 0, v44, s[0:1]
	v_cmp_ge_u32_e64 s[0:1], v31, v43
	v_addc_co_u32_e64 v44, s[2:3], 0, v44, s[2:3]
	v_addc_co_u32_e64 v44, vcc, 0, v44, vcc
	v_addc_co_u32_e64 v44, s[0:1], 0, v44, s[0:1]
	v_mov_b32_e32 v45, v44
	s_nop 1
	v_add_u32_dpp v45, v45, v45 row_ror:1 row_mask:0xf bank_mask:0xf
	s_nop 1
	v_add_u32_dpp v45, v45, v45 row_ror:2 row_mask:0xf bank_mask:0xf
	s_nop 1
	v_add_u32_dpp v45, v45, v45 row_ror:4 row_mask:0xf bank_mask:0xf
	s_nop 1
	v_add_u32_dpp v45, v45, v45 row_ror:8 row_mask:0xf bank_mask:0xf
	s_nop 0
	v_cmp_le_u32_e32 vcc, 0x100, v45
	s_nop 1
	v_cndmask_b32_e32 v36, v36, v42, vcc
	v_cndmask_b32_e32 v46, v46, v45, vcc
	v_cndmask_b32_e32 v47, v47, v44, vcc
	v_or_b32_e32 v42, 1, v36
	v_lshlrev_b32_e32 v41, v39, v42
	v_add_u32_e64 v43, v34, v41 clamp
	v_mov_b32_e32 v44, 0
	v_cmp_ge_u32_e32 vcc, v0, v43
	v_cmp_ge_u32_e64 s[0:1], v1, v43
	v_cmp_ge_u32_e64 s[2:3], v2, v43
	v_addc_co_u32_e64 v44, vcc, 0, v44, vcc
	v_cmp_ge_u32_e32 vcc, v3, v43
	v_addc_co_u32_e64 v44, s[0:1], 0, v44, s[0:1]
	v_cmp_ge_u32_e64 s[0:1], v4, v43
	v_addc_co_u32_e64 v44, s[2:3], 0, v44, s[2:3]
	v_cmp_ge_u32_e64 s[2:3], v5, v43
	v_addc_co_u32_e64 v44, vcc, 0, v44, vcc
	v_cmp_ge_u32_e32 vcc, v6, v43
	v_addc_co_u32_e64 v44, s[0:1], 0, v44, s[0:1]
	v_cmp_ge_u32_e64 s[0:1], v7, v43
	v_addc_co_u32_e64 v44, s[2:3], 0, v44, s[2:3]
	v_cmp_ge_u32_e64 s[2:3], v8, v43
	v_addc_co_u32_e64 v44, vcc, 0, v44, vcc
	v_cmp_ge_u32_e32 vcc, v9, v43
	v_addc_co_u32_e64 v44, s[0:1], 0, v44, s[0:1]
	v_cmp_ge_u32_e64 s[0:1], v10, v43
	v_addc_co_u32_e64 v44, s[2:3], 0, v44, s[2:3]
	v_cmp_ge_u32_e64 s[2:3], v11, v43
	v_addc_co_u32_e64 v44, vcc, 0, v44, vcc
	v_cmp_ge_u32_e32 vcc, v12, v43
	v_addc_co_u32_e64 v44, s[0:1], 0, v44, s[0:1]
	v_cmp_ge_u32_e64 s[0:1], v13, v43
	v_addc_co_u32_e64 v44, s[2:3], 0, v44, s[2:3]
	v_cmp_ge_u32_e64 s[2:3], v14, v43
	v_addc_co_u32_e64 v44, vcc, 0, v44, vcc
	v_cmp_ge_u32_e32 vcc, v15, v43
	v_addc_co_u32_e64 v44, s[0:1], 0, v44, s[0:1]
	v_cmp_ge_u32_e64 s[0:1], v16, v43
	v_addc_co_u32_e64 v44, s[2:3], 0, v44, s[2:3]
	v_cmp_ge_u32_e64 s[2:3], v17, v43
	v_addc_co_u32_e64 v44, vcc, 0, v44, vcc
	v_cmp_ge_u32_e32 vcc, v18, v43
	v_addc_co_u32_e64 v44, s[0:1], 0, v44, s[0:1]
	v_cmp_ge_u32_e64 s[0:1], v19, v43
	v_addc_co_u32_e64 v44, s[2:3], 0, v44, s[2:3]
	v_cmp_ge_u32_e64 s[2:3], v20, v43
	v_addc_co_u32_e64 v44, vcc, 0, v44, vcc
	v_cmp_ge_u32_e32 vcc, v21, v43
	v_addc_co_u32_e64 v44, s[0:1], 0, v44, s[0:1]
	v_cmp_ge_u32_e64 s[0:1], v22, v43
	v_addc_co_u32_e64 v44, s[2:3], 0, v44, s[2:3]
	v_cmp_ge_u32_e64 s[2:3], v23, v43
	v_addc_co_u32_e64 v44, vcc, 0, v44, vcc
	v_cmp_ge_u32_e32 vcc, v24, v43
	v_addc_co_u32_e64 v44, s[0:1], 0, v44, s[0:1]
	v_cmp_ge_u32_e64 s[0:1], v25, v43
	v_addc_co_u32_e64 v44, s[2:3], 0, v44, s[2:3]
	v_cmp_ge_u32_e64 s[2:3], v26, v43
	v_addc_co_u32_e64 v44, vcc, 0, v44, vcc
	v_cmp_ge_u32_e32 vcc, v27, v43
	v_addc_co_u32_e64 v44, s[0:1], 0, v44, s[0:1]
	v_cmp_ge_u32_e64 s[0:1], v28, v43
	v_addc_co_u32_e64 v44, s[2:3], 0, v44, s[2:3]
	v_cmp_ge_u32_e64 s[2:3], v29, v43
	v_addc_co_u32_e64 v44, vcc, 0, v44, vcc
	v_cmp_ge_u32_e32 vcc, v30, v43
	v_addc_co_u32_e64 v44, s[0:1], 0, v44, s[0:1]
	v_cmp_ge_u32_e64 s[0:1], v31, v43
	v_addc_co_u32_e64 v44, s[2:3], 0, v44, s[2:3]
	v_addc_co_u32_e64 v44, vcc, 0, v44, vcc
	v_addc_co_u32_e64 v44, s[0:1], 0, v44, s[0:1]
	v_mov_b32_e32 v45, v44
	s_nop 1
	v_add_u32_dpp v45, v45, v45 row_ror:1 row_mask:0xf bank_mask:0xf
	s_nop 1
	v_add_u32_dpp v45, v45, v45 row_ror:2 row_mask:0xf bank_mask:0xf
	s_nop 1
	v_add_u32_dpp v45, v45, v45 row_ror:4 row_mask:0xf bank_mask:0xf
	s_nop 1
	v_add_u32_dpp v45, v45, v45 row_ror:8 row_mask:0xf bank_mask:0xf
	s_nop 0
	v_cmp_le_u32_e32 vcc, 0x100, v45
	s_nop 1
	v_cndmask_b32_e32 v36, v36, v42, vcc
	v_cndmask_b32_e32 v46, v46, v45, vcc
	v_cndmask_b32_e32 v47, v47, v44, vcc
	v_lshlrev_b32_e32 v41, v39, v36
	v_add_u32_e32 v41, v34, v41
	v_cmp_ge_u32_e32 vcc, 0x140, v46
	v_cmp_eq_u32_e64 s[0:1], 0, v39
	v_lshlrev_b32_e32 v42, v39, v200
	v_add_u32_e32 v42, -1, v42
	s_or_b64 vcc, vcc, s[0:1]
	s_andn2_b64 s[0:1], vcc, s[50:51]
	s_nor_b64 s[2:3], vcc, s[50:51]
	s_or_b64 s[50:51], s[50:51], vcc
	v_add_u32_e64 v42, v41, v42 clamp
	v_min_u32_e32 v42, v42, v35
	v_cndmask_b32_e64 v37, v37, v41, s[0:1]
	v_cndmask_b32_e64 v62, v62, v47, s[0:1]
	v_cndmask_b32_e64 v35, v35, v42, s[2:3]
	v_cndmask_b32_e64 v34, v34, v41, s[2:3]
	s_cmp_eq_u64 s[50:51], -1
	s_cbranch_scc0 .Lp2apr1_iter
	s_mov_b64 exec, s[22:23]
	v_mov_b32_e32 v61, v62
	s_nop 1
	v_add_u32_dpp v61, v61, v61 row_shr:1 row_mask:0xf bank_mask:0xf bound_ctrl:1
	s_nop 1
	v_add_u32_dpp v61, v61, v61 row_shr:2 row_mask:0xf bank_mask:0xf bound_ctrl:1
	s_nop 1
	v_add_u32_dpp v61, v61, v61 row_shr:4 row_mask:0xf bank_mask:0xf bound_ctrl:1
	s_nop 1
	v_add_u32_dpp v61, v61, v61 row_shr:8 row_mask:0xf bank_mask:0xf bound_ctrl:1
	v_sub_u32_e32 v62, v61, v62
	v_lshl_add_u32 v41, v62, 2, v59
	v_cmpx_ge_u32_e32 vcc, v0, v37
	ds_write_b32 v41, v0
	v_add_u32_e32 v62, 1, v62
	s_mov_b64 exec, s[22:23]
	v_lshl_add_u32 v41, v62, 2, v59
	v_cmpx_ge_u32_e32 vcc, v1, v37
	ds_write_b32 v41, v1
	v_add_u32_e32 v62, 1, v62
	s_mov_b64 exec, s[22:23]
	v_lshl_add_u32 v41, v62, 2, v59
	v_cmpx_ge_u32_e32 vcc, v2, v37
	ds_write_b32 v41, v2
	v_add_u32_e32 v62, 1, v62
	s_mov_b64 exec, s[22:23]
	v_lshl_add_u32 v41, v62, 2, v59
	v_cmpx_ge_u32_e32 vcc, v3, v37
	ds_write_b32 v41, v3
	v_add_u32_e32 v62, 1, v62
	s_mov_b64 exec, s[22:23]
	v_lshl_add_u32 v41, v62, 2, v59
	v_cmpx_ge_u32_e32 vcc, v4, v37
	ds_write_b32 v41, v4
	v_add_u32_e32 v62, 1, v62
	s_mov_b64 exec, s[22:23]
	v_lshl_add_u32 v41, v62, 2, v59
	v_cmpx_ge_u32_e32 vcc, v5, v37
	ds_write_b32 v41, v5
	v_add_u32_e32 v62, 1, v62
	s_mov_b64 exec, s[22:23]
	v_lshl_add_u32 v41, v62, 2, v59
	v_cmpx_ge_u32_e32 vcc, v6, v37
	ds_write_b32 v41, v6
	v_add_u32_e32 v62, 1, v62
	s_mov_b64 exec, s[22:23]
	v_lshl_add_u32 v41, v62, 2, v59
	v_cmpx_ge_u32_e32 vcc, v7, v37
	ds_write_b32 v41, v7
	v_add_u32_e32 v62, 1, v62
	s_mov_b64 exec, s[22:23]
	v_lshl_add_u32 v41, v62, 2, v59
	v_cmpx_ge_u32_e32 vcc, v8, v37
	ds_write_b32 v41, v8
	v_add_u32_e32 v62, 1, v62
	s_mov_b64 exec, s[22:23]
	v_lshl_add_u32 v41, v62, 2, v59
	v_cmpx_ge_u32_e32 vcc, v9, v37
	ds_write_b32 v41, v9
	v_add_u32_e32 v62, 1, v62
	s_mov_b64 exec, s[22:23]
	v_lshl_add_u32 v41, v62, 2, v59
	v_cmpx_ge_u32_e32 vcc, v10, v37
	ds_write_b32 v41, v10
	v_add_u32_e32 v62, 1, v62
	s_mov_b64 exec, s[22:23]
	v_lshl_add_u32 v41, v62, 2, v59
	v_cmpx_ge_u32_e32 vcc, v11, v37
	ds_write_b32 v41, v11
	v_add_u32_e32 v62, 1, v62
	s_mov_b64 exec, s[22:23]
	v_lshl_add_u32 v41, v62, 2, v59
	v_cmpx_ge_u32_e32 vcc, v12, v37
	ds_write_b32 v41, v12
	v_add_u32_e32 v62, 1, v62
	s_mov_b64 exec, s[22:23]
	v_lshl_add_u32 v41, v62, 2, v59
	v_cmpx_ge_u32_e32 vcc, v13, v37
	ds_write_b32 v41, v13
	v_add_u32_e32 v62, 1, v62
	s_mov_b64 exec, s[22:23]
	v_lshl_add_u32 v41, v62, 2, v59
	v_cmpx_ge_u32_e32 vcc, v14, v37
	ds_write_b32 v41, v14
	v_add_u32_e32 v62, 1, v62
	s_mov_b64 exec, s[22:23]
	v_lshl_add_u32 v41, v62, 2, v59
	v_cmpx_ge_u32_e32 vcc, v15, v37
	ds_write_b32 v41, v15
	v_add_u32_e32 v62, 1, v62
	s_mov_b64 exec, s[22:23]
	v_lshl_add_u32 v41, v62, 2, v59
	v_cmpx_ge_u32_e32 vcc, v16, v37
	ds_write_b32 v41, v16
	v_add_u32_e32 v62, 1, v62
	s_mov_b64 exec, s[22:23]
	v_lshl_add_u32 v41, v62, 2, v59
	v_cmpx_ge_u32_e32 vcc, v17, v37
	ds_write_b32 v41, v17
	v_add_u32_e32 v62, 1, v62
	s_mov_b64 exec, s[22:23]
	v_lshl_add_u32 v41, v62, 2, v59
	v_cmpx_ge_u32_e32 vcc, v18, v37
	ds_write_b32 v41, v18
	v_add_u32_e32 v62, 1, v62
	s_mov_b64 exec, s[22:23]
	v_lshl_add_u32 v41, v62, 2, v59
	v_cmpx_ge_u32_e32 vcc, v19, v37
	ds_write_b32 v41, v19
	v_add_u32_e32 v62, 1, v62
	s_mov_b64 exec, s[22:23]
	v_lshl_add_u32 v41, v62, 2, v59
	v_cmpx_ge_u32_e32 vcc, v20, v37
	ds_write_b32 v41, v20
	v_add_u32_e32 v62, 1, v62
	s_mov_b64 exec, s[22:23]
	v_lshl_add_u32 v41, v62, 2, v59
	v_cmpx_ge_u32_e32 vcc, v21, v37
	ds_write_b32 v41, v21
	v_add_u32_e32 v62, 1, v62
	s_mov_b64 exec, s[22:23]
	v_lshl_add_u32 v41, v62, 2, v59
	v_cmpx_ge_u32_e32 vcc, v22, v37
	ds_write_b32 v41, v22
	v_add_u32_e32 v62, 1, v62
	s_mov_b64 exec, s[22:23]
	v_lshl_add_u32 v41, v62, 2, v59
	v_cmpx_ge_u32_e32 vcc, v23, v37
	ds_write_b32 v41, v23
	v_add_u32_e32 v62, 1, v62
	s_mov_b64 exec, s[22:23]
	v_lshl_add_u32 v41, v62, 2, v59
	v_cmpx_ge_u32_e32 vcc, v24, v37
	ds_write_b32 v41, v24
	v_add_u32_e32 v62, 1, v62
	s_mov_b64 exec, s[22:23]
	v_lshl_add_u32 v41, v62, 2, v59
	v_cmpx_ge_u32_e32 vcc, v25, v37
	ds_write_b32 v41, v25
	v_add_u32_e32 v62, 1, v62
	s_mov_b64 exec, s[22:23]
	v_lshl_add_u32 v41, v62, 2, v59
	v_cmpx_ge_u32_e32 vcc, v26, v37
	ds_write_b32 v41, v26
	v_add_u32_e32 v62, 1, v62
	s_mov_b64 exec, s[22:23]
	v_lshl_add_u32 v41, v62, 2, v59
	v_cmpx_ge_u32_e32 vcc, v27, v37
	ds_write_b32 v41, v27
	v_add_u32_e32 v62, 1, v62
	s_mov_b64 exec, s[22:23]
	v_lshl_add_u32 v41, v62, 2, v59
	v_cmpx_ge_u32_e32 vcc, v28, v37
	ds_write_b32 v41, v28
	v_add_u32_e32 v62, 1, v62
	s_mov_b64 exec, s[22:23]
	v_lshl_add_u32 v41, v62, 2, v59
	v_cmpx_ge_u32_e32 vcc, v29, v37
	ds_write_b32 v41, v29
	v_add_u32_e32 v62, 1, v62
	s_mov_b64 exec, s[22:23]
	v_lshl_add_u32 v41, v62, 2, v59
	v_cmpx_ge_u32_e32 vcc, v30, v37
	ds_write_b32 v41, v30
	v_add_u32_e32 v62, 1, v62
	s_mov_b64 exec, s[22:23]
	v_lshl_add_u32 v41, v62, 2, v59
	v_cmpx_ge_u32_e32 vcc, v31, v37
	ds_write_b32 v41, v31
	v_add_u32_e32 v62, 1, v62
	s_mov_b64 exec, s[22:23]
	s_mov_b64 exec, -1
	v_and_b32_e32 v41, 0xffffe000, v37
	v_ashrrev_i32_e32 v42, 31, v41
	v_not_b32_e32 v42, v42
	v_or_b32_e32 v42, 0x80000000, v42
	v_xor_b32_e32 v63, v41, v42
	s_cmpk_lt_i32 s8, 0x141
	s_cbranch_scc1 .Lp2apr1_o0
	v_readlane_b32 s0, v63, 0
	v_readlane_b32 s74, v37, 0
	v_readlane_b32 s8, v61, 15
	v_mov_b32_e32 v233, s0

.Lp2apr1_o3:
.Lp2apr1_end:
	s_lshl_b32 s0, s78, 2
	s_add_u32 s0, s0, s33
	s_add_u32 s0, s0, 0x0
	s_lshl_b32 s1, s16, 2
	s_add_u32 s1, s1, s33
	s_add_u32 s1, s1, 0x1000
	v_mov_b32_e32 v238, s1
	v_mov_b32_e32 v243, s0
	v_cndmask_b32_e64 v238, v238, v243, s[40:41]
	s_lshl_b32 s0, s61, 2
	s_add_u32 s0, s0, s33
	s_add_u32 s0, s0, 0x800
	s_lshl_b32 s1, s15, 2
	s_add_u32 s1, s1, s33
	s_add_u32 s1, s1, 0x1800
	v_mov_b32_e32 v239, s1
	v_mov_b32_e32 v243, s0
	v_cndmask_b32_e64 v239, v239, v243, s[40:41]
	s_lshl_b32 s0, s8, 2
	s_add_u32 s0, s0, s33
	s_add_u32 s0, s0, 0x2000
	s_lshl_b32 s1, s13, 2
	s_add_u32 s1, s1, s33
	s_add_u32 s1, s1, 0x3000
	v_mov_b32_e32 v240, s1
	v_mov_b32_e32 v243, s0
	v_cndmask_b32_e64 v240, v240, v243, s[40:41]
	s_lshl_b32 s0, s14, 2
	s_add_u32 s0, s0, s33
	s_add_u32 s0, s0, 0x2800
	s_lshl_b32 s1, s5, 2
	s_add_u32 s1, s1, s33
	s_add_u32 s1, s1, 0x3800
	v_mov_b32_e32 v241, s1
	v_mov_b32_e32 v243, s0
	v_cndmask_b32_e64 v241, v241, v243, s[40:41]

.LBB0_1066:
	s_nop 0
	v_readlane_b32 s0, v238, 0
	v_readlane_b32 s1, v238, 32
	s_sub_u32 s0, s0, s33
	s_sub_u32 s0, s0, 0x0
	s_lshr_b32 s78, s0, 2
	s_sub_u32 s1, s1, s33
	s_sub_u32 s1, s1, 0x1000
	s_lshr_b32 s16, s1, 2
	v_readlane_b32 s0, v239, 0
	v_readlane_b32 s1, v239, 32
	s_sub_u32 s0, s0, s33
	s_sub_u32 s0, s0, 0x800
	s_lshr_b32 s61, s0, 2
	s_sub_u32 s1, s1, s33
	s_sub_u32 s1, s1, 0x1800
	s_lshr_b32 s15, s1, 2
	v_readlane_b32 s0, v240, 0
	v_readlane_b32 s1, v240, 32
	s_sub_u32 s0, s0, s33
	s_sub_u32 s0, s0, 0x2000
	s_lshr_b32 s8, s0, 2
	s_sub_u32 s1, s1, s33
	s_sub_u32 s1, s1, 0x3000
	s_lshr_b32 s13, s1, 2
	v_readlane_b32 s0, v241, 0
	v_readlane_b32 s1, v241, 32
	s_sub_u32 s0, s0, s33
	s_sub_u32 s0, s0, 0x2800
	s_lshr_b32 s14, s0, 2
	s_sub_u32 s1, s1, s33
	s_sub_u32 s1, s1, 0x3800
	s_lshr_b32 s5, s1, 2
	s_and_b32 s0, s73, 0xffffe000
	s_and_b32 s66, s72, 0xffffe000
	s_and_b32 s63, s71, 0xffffe000
	s_and_b32 s51, s70, 0xffffe000
	s_and_b32 s50, s74, 0xffffe000
	s_and_b32 s23, s75, 0xffffe000
	s_and_b32 s22, s76, 0xffffe000
	s_and_b32 s9, s77, 0xffffe000
	s_andn2_b64 vcc, exec, s[64:65]
	s_cbranch_vccnz .LBB0_567
	s_branch .LBB0_1068
